# GEMM loops: the four per-iteration LDS fragment-base VALU adds folded into ds_read immediates (lane-offset register biased once at its definition); five of six loops
# speedup vs baseline: 1.0465x; 1.0020x over previous
; #define PG8_STAGE(bufoff, gbase, voff) do { _Pragma("unroll") for (int _i = 0; _i < 2; ++_i) \
;         __builtin_amdgcn_global_load_lds((const unsigned*)((const char*)(gbase) + (voff)[_i]), (LAS unsigned*)(lds + (bufoff) + ldsw + _i * 8192), 16, 0, 0); } while (0)
; #define PG8_WAIT_V(n) asm volatile("s_waitcnt vmcnt(" #n ")" ::: "memory")
; #define PG8_BAR __builtin_amdgcn_s_barrier()
; template <class Epi>
; __device__ __forceinline__ void gemm_phase(LAS unsigned char* lds, const Gemm g, const StaticOrder& S, const Epi& E) {
;     ...
;     const int aoff = lds_byte(wr * 64 + fr, fq * 8), boff = lds_byte(wc * 32 + fr, fq * 8);
;     ...
;     Unit cur, nxt; int ui = 0;
;     if (!S.next(0, cur)) return;
;     f32x4 acc[2][2][4][2];
; #pragma unroll
;     for (int a = 0; a < 2; ++a)
; #pragma unroll
;         for (int b = 0; b < 2; ++b)
; #pragma unroll
;             for (int m = 0; m < 4; ++m)
; #pragma unroll
;                 for (int n = 0; n < 2; ++n) acc[a][b][m][n] = (f32x4){0.f, 0.f, 0.f, 0.f};
;     bf16x8 At[4][2], B0[2][2], B1[2][2];
;     const char* cA = (const char*)g.A + (size_t)cur.pm * tstep; const char* cB = (const char*)g.Bt + (size_t)cur.pn * tstep;
;     PG8_STAGE(PG8_SB(0, 0), cB, voffB); PG8_STAGE(PG8_SA(0, 0), cA, voffA); PG8_STAGE(PG8_SB(0, 1), cB + hstep, voffB); PG8_STAGE(PG8_SA(0, 1), cA + hstep, voffA);
;     if (wr == 1) PG8_BAR;
;     PG8_WAIT_V(4); PG8_BAR;
;     PG8_STAGE(PG8_SB(1, 0), cB + kstep, voffB); PG8_STAGE(PG8_SA(1, 0), cA + kstep, voffA); PG8_STAGE(PG8_SB(1, 1), cB + hstep + kstep, voffB);
;     PG8_WAIT_V(6); PG8_BAR;
.LBB0_38:
	s_and_b64 s[10:11], s[0:1], exec
	v_lshrrev_b32_e32 v16, 1, v12
	s_cselect_b32 s7, 0x1000, 0
	v_and_b32_e32 v16, 24, v16
	s_add_u32 s10, s92, s7
	v_and_b32_e32 v15, 15, v12
	v_lshlrev_b32_e32 v17, 1, v16
	v_lshlrev_b32_e32 v12, 2, v12
	s_addc_u32 s11, s93, 0
	v_lshl_or_b32 v187, s3, 6, v15
	v_lshl_or_b32 v15, v15, 6, v17
	s_lshl_b32 s3, s3, 13
	v_and_b32_e32 v12, 32, v12
	v_bitop3_b32 v17, v15, s3, v12 bitop3:0xde
	s_lshl_b32 s3, s6, 5
	s_and_b32 s3, s3, 0x60
	s_add_i32 m0, s21, 0x18000
	v_lshl_add_u64 v[6:7], v[6:7], 0, s[58:59]
	s_lshl_b32 s6, s3, 7
	s_waitcnt vmcnt(4)
	s_barrier
	global_load_lds_dwordx4 v[6:7], off
	v_lshl_add_u64 v[4:5], v[4:5], 0, s[58:59]
	s_add_i32 m0, s21, 0x1a000
	s_add_i32 s41, s21, 0x8000
	s_add_i32 s42, s21, 0xa000
	v_bitop3_b32 v247, v15, s6, v12 bitop3:0xde
	v_add_u32_e32 v247, 0x10000, v247
	global_load_lds_dwordx4 v[4:5], off
	v_lshl_add_u64 v[2:3], v[2:3], 0, s[58:59]
	s_mov_b32 m0, s41
	s_add_u32 s6, s24, 0x40080
	global_load_lds_dwordx4 v[2:3], off
	v_lshl_add_u64 v[0:1], v[0:1], 0, s[58:59]
	s_mov_b32 m0, s42
	s_addc_u32 s7, s25, 0
	global_load_lds_dwordx4 v[0:1], off
	s_add_i32 m0, s21, 0x1c000
	v_lshl_add_u64 v[0:1], s[6:7], 0, v[184:185]
	global_load_lds_dwordx4 v[0:1], off
	v_lshl_add_u64 v[0:1], s[6:7], 0, v[212:213]
	s_add_i32 m0, s21, 0x1e000
	s_mov_b32 s40, 0
	global_load_lds_dwordx4 v[0:1], off
	v_lshlrev_b32_e32 v0, 14, v8
	v_and_b32_e32 v0, 0xffff8000, v0
	v_lshl_add_u32 v0, v9, 11, v0
	v_and_b32_e32 v1, 1, v8
	v_lshl_or_b32 v0, v1, 6, v0
	v_lshl_add_u32 v214, v10, 1, v0
	v_lshlrev_b32_e32 v0, 14, v11
	v_and_b32_e32 v0, 0xffff8000, v0
	s_waitcnt vmcnt(6)
	v_lshl_add_u32 v0, v13, 11, v0
	v_and_b32_e32 v1, 1, v11
	v_lshl_or_b32 v0, v1, 6, v0
	s_ashr_i32 s44, s28, 31
	v_or_b32_e32 v248, s3, v16
	v_mov_b32_e32 v215, v185
	v_lshl_add_u32 v216, v14, 1, v0
	v_mov_b32_e32 v217, v185
	v_add_u32_e32 v249, 0, v17
	s_barrier
	s_branch .LBB0_40

; #define PG8_STAGE(bufoff, gbase, voff) do { _Pragma("unroll") for (int _i = 0; _i < 2; ++_i) \
;         __builtin_amdgcn_global_load_lds((const unsigned*)((const char*)(gbase) + (voff)[_i]), (LAS unsigned*)(lds + (bufoff) + ldsw + _i * 8192), 16, 0, 0); } while (0)
; #define PG8_LDA(dst, b, h) do { _Pragma("unroll") for (int m = 0; m < 4; ++m) _Pragma("unroll") for (int k = 0; k < 2; ++k) dst[m][k] = *(const LAS bf16x8*)(lds + PG8_SA(b, h) + aoff + m * 2048 + k * 1024); } while (0)
; #define PG8_LDB(dst, b, h) do { _Pragma("unroll") for (int n = 0; n < 2; ++n) _Pragma("unroll") for (int k = 0; k < 2; ++k) dst[n][k] = *(const LAS bf16x8*)(lds + PG8_SB(b, h) + boff + n * 2048 + k * 1024); } while (0)
; #define PG8_MMA(ai, bj, At, Bt) do { __builtin_amdgcn_s_setprio(1); _Pragma("unroll") for (int m = 0; m < 4; ++m) _Pragma("unroll") for (int n = 0; n < 2; ++n) _Pragma("unroll") for (int k = 0; k < 2; ++k) \
;         acc[ai][bj][m][n] = __builtin_amdgcn_mfma_f32_16x16x32_bf16(Bt[n][k], At[m][k], acc[ai][bj][m][n], 0, 0, 0); __builtin_amdgcn_s_setprio(0); } while (0)
; #define PG8_WAIT_V(n) asm volatile("s_waitcnt vmcnt(" #n ")" ::: "memory")
; #define PG8_WAIT_L(n) asm volatile("s_waitcnt lgkmcnt(" #n ")" ::: "memory")
; template <class Epi>
; __device__ __forceinline__ void gemm_phase(LAS unsigned char* lds, const Gemm g, const StaticOrder& S, const Epi& E) {
;     ...
;         for (int t = 0; t < nt; t += 2) {
;             const bool last = (t == nt - 2);
;             const char* a1 = cA + (size_t)(t + 1) * kstep;
;             const char* a2 = last ? nA : cA + (size_t)(t + 2) * kstep; const char* b2 = last ? nB : cB + (size_t)(t + 2) * kstep;
;             const char* a3 = a2 + kstep; const char* b3 = b2 + kstep;
;             PG8_LDB(B0, 0, 0); PG8_SCHED; PG8_LDA(At, 0, 0); PG8_STAGE(PG8_SA(1, 1), a1 + hstep, voffA);
;             PG8_WAIT_L(8); PG8_BAR; PG8_WAIT_L(0); PG8_MMA(0, 0, At, B0); PG8_BAR; PG8_SCHED;
;             PG8_LDB(B1, 0, 1); PG8_STAGE(PG8_SB(0, 0), b2, voffB);
;             PG8_BAR; PG8_WAIT_L(0); PG8_MMA(0, 1, At, B1); PG8_BAR;
;             PG8_LDA(At, 0, 1); PG8_STAGE(PG8_SA(0, 0), a2, voffA);
;             PG8_BAR; PG8_WAIT_L(0); PG8_MMA(1, 0, At, B0); PG8_BAR; PG8_SCHED;
;             PG8_STAGE(PG8_SB(0, 1), b2 + hstep, voffB);
;             PG8_WAIT_V(6); PG8_BAR; PG8_MMA(1, 1, At, B1); PG8_BAR;
.LBB0_43:
	s_add_u32 s24, s22, 0xfffc0080
	s_addc_u32 s25, s23, -1
	s_add_i32 s47, 0, 0x10000
	ds_read_b128 v[128:131], v247
	ds_read_b128 v[132:135], v247 offset:1024
	ds_read_b128 v[136:139], v247 offset:2048
	ds_read_b128 v[140:143], v247 offset:3072
	s_cmp_eq_u32 s46, 12
	s_cselect_b32 s27, s3, s25
	s_cselect_b32 s26, s9, s24
	s_cselect_b32 s25, s13, s45
	s_cselect_b32 s24, s15, s43
	s_add_i32 m0, s21, 0xc000
	ds_read_b128 v[144:147], v249
	ds_read_b128 v[148:151], v249 offset:1024
	ds_read_b128 v[152:155], v249 offset:2048
	ds_read_b128 v[156:159], v249 offset:3072
	ds_read_b128 v[160:163], v249 offset:4096
	ds_read_b128 v[164:167], v249 offset:5120
	ds_read_b128 v[168:171], v249 offset:6144
	ds_read_b128 v[172:175], v249 offset:7168
	global_load_lds_dwordx4 v214, s[22:23]
	s_add_i32 m0, s21, 0xe000
	s_nop 0
	global_load_lds_dwordx4 v216, s[22:23]
	s_waitcnt lgkmcnt(8)
	s_barrier
	s_waitcnt lgkmcnt(0)
	s_waitcnt lgkmcnt(0)
	v_mfma_f32_16x16x32_bf16 v[124:127], v[128:131], v[144:147], v[124:127]
	v_mfma_f32_16x16x32_bf16 v[124:127], v[132:135], v[148:151], v[124:127]
	v_mfma_f32_16x16x32_bf16 v[108:111], v[128:131], v[152:155], v[108:111]
	v_mfma_f32_16x16x32_bf16 v[108:111], v[132:135], v[156:159], v[108:111]
	v_mfma_f32_16x16x32_bf16 v[92:95], v[128:131], v[160:163], v[92:95]
	v_mfma_f32_16x16x32_bf16 v[92:95], v[132:135], v[164:167], v[92:95]
	v_mfma_f32_16x16x32_bf16 v[76:79], v[128:131], v[168:171], v[76:79]
	v_mfma_f32_16x16x32_bf16 v[76:79], v[132:135], v[172:175], v[76:79]
	v_mfma_f32_16x16x32_bf16 v[72:75], v[136:139], v[168:171], v[72:75]
	v_mfma_f32_16x16x32_bf16 v[72:75], v[140:143], v[172:175], v[72:75]
	v_mfma_f32_16x16x32_bf16 v[88:91], v[136:139], v[160:163], v[88:91]
	v_mfma_f32_16x16x32_bf16 v[88:91], v[140:143], v[164:167], v[88:91]
	v_mfma_f32_16x16x32_bf16 v[104:107], v[136:139], v[152:155], v[104:107]
	v_mfma_f32_16x16x32_bf16 v[104:107], v[140:143], v[156:159], v[104:107]
	v_mfma_f32_16x16x32_bf16 v[120:123], v[136:139], v[144:147], v[120:123]
	v_mfma_f32_16x16x32_bf16 v[120:123], v[140:143], v[148:151], v[120:123]
	s_barrier
	s_add_i32 s52, 0, 0x14000
	s_add_i32 s47, s47, s36
	ds_read_b128 v[176:179], v247 offset:16384
	ds_read_b128 v[180:183], v247 offset:17408
	ds_read_b128 v[204:207], v247 offset:18432
	ds_read_b128 v[218:221], v247 offset:19456
	s_mov_b32 m0, s47
	s_add_u32 s98, s24, s58
	s_addc_u32 s99, s25, s59
	global_load_lds_dwordx4 v184, s[24:25]
	s_add_i32 m0, s47, 0x2000
	s_nop 0
	global_load_lds_dwordx4 v212, s[24:25]
	s_barrier
	s_waitcnt lgkmcnt(0)
	s_waitcnt lgkmcnt(0)
	v_mfma_f32_16x16x32_bf16 v[116:119], v[176:179], v[144:147], v[116:119]
	v_mfma_f32_16x16x32_bf16 v[116:119], v[180:183], v[148:151], v[116:119]
	v_mfma_f32_16x16x32_bf16 v[100:103], v[176:179], v[152:155], v[100:103]
	v_mfma_f32_16x16x32_bf16 v[100:103], v[180:183], v[156:159], v[100:103]
	v_mfma_f32_16x16x32_bf16 v[84:87], v[176:179], v[160:163], v[84:87]
	v_mfma_f32_16x16x32_bf16 v[84:87], v[180:183], v[164:167], v[84:87]
	v_mfma_f32_16x16x32_bf16 v[68:71], v[176:179], v[168:171], v[68:71]
	v_mfma_f32_16x16x32_bf16 v[68:71], v[180:183], v[172:175], v[68:71]
	v_mfma_f32_16x16x32_bf16 v[64:67], v[204:207], v[168:171], v[64:67]
	v_mfma_f32_16x16x32_bf16 v[64:67], v[218:221], v[172:175], v[64:67]
	v_mfma_f32_16x16x32_bf16 v[80:83], v[204:207], v[160:163], v[80:83]
	v_mfma_f32_16x16x32_bf16 v[80:83], v[218:221], v[164:167], v[80:83]
	v_mfma_f32_16x16x32_bf16 v[96:99], v[204:207], v[152:155], v[96:99]
	v_mfma_f32_16x16x32_bf16 v[96:99], v[218:221], v[156:159], v[96:99]
	v_mfma_f32_16x16x32_bf16 v[112:115], v[204:207], v[144:147], v[112:115]
	v_mfma_f32_16x16x32_bf16 v[112:115], v[218:221], v[148:151], v[112:115]
	s_mov_b32 m0, s21
	s_barrier
	ds_read_b128 v[144:147], v249 offset:16384
	ds_read_b128 v[148:151], v249 offset:17408
	ds_read_b128 v[152:155], v249 offset:18432
	ds_read_b128 v[156:159], v249 offset:19456
	ds_read_b128 v[160:163], v249 offset:20480
	ds_read_b128 v[164:167], v249 offset:21504
	ds_read_b128 v[168:171], v249 offset:22528
	ds_read_b128 v[172:175], v249 offset:23552
	global_load_lds_dwordx4 v208, s[26:27]
	s_add_u32 s100, s26, s58
	s_addc_u32 s101, s27, s59
	s_mov_b32 m0, s37
	s_nop 0
	global_load_lds_dwordx4 v210, s[26:27]
	s_barrier
	s_waitcnt lgkmcnt(0)
	s_waitcnt lgkmcnt(0)
	v_mfma_f32_16x16x32_bf16 v[60:63], v[128:131], v[144:147], v[60:63]
	v_mfma_f32_16x16x32_bf16 v[60:63], v[132:135], v[148:151], v[60:63]
	v_mfma_f32_16x16x32_bf16 v[44:47], v[128:131], v[152:155], v[44:47]
	v_mfma_f32_16x16x32_bf16 v[44:47], v[132:135], v[156:159], v[44:47]
	v_mfma_f32_16x16x32_bf16 v[28:31], v[128:131], v[160:163], v[28:31]
	v_mfma_f32_16x16x32_bf16 v[28:31], v[132:135], v[164:167], v[28:31]
	v_mfma_f32_16x16x32_bf16 v[16:19], v[128:131], v[168:171], v[16:19]
	v_mfma_f32_16x16x32_bf16 v[16:19], v[132:135], v[172:175], v[16:19]
	v_mfma_f32_16x16x32_bf16 v[8:11], v[136:139], v[168:171], v[8:11]
	v_mfma_f32_16x16x32_bf16 v[8:11], v[140:143], v[172:175], v[8:11]
	v_mfma_f32_16x16x32_bf16 v[24:27], v[136:139], v[160:163], v[24:27]
	v_mfma_f32_16x16x32_bf16 v[24:27], v[140:143], v[164:167], v[24:27]
	v_mfma_f32_16x16x32_bf16 v[40:43], v[136:139], v[152:155], v[40:43]
	v_mfma_f32_16x16x32_bf16 v[40:43], v[140:143], v[156:159], v[40:43]
	v_mfma_f32_16x16x32_bf16 v[56:59], v[136:139], v[144:147], v[56:59]
	v_mfma_f32_16x16x32_bf16 v[56:59], v[140:143], v[148:151], v[56:59]
	s_barrier
	s_add_u32 s50, s24, 0x40000
	s_addc_u32 s51, s25, 0
	s_add_i32 s47, s52, s36
	s_mov_b32 m0, s47
	s_nop 0
	global_load_lds_dwordx4 v184, s[50:51]
	s_add_i32 m0, s47, 0x2000
	s_nop 0
	global_load_lds_dwordx4 v212, s[50:51]
	s_waitcnt vmcnt(6)
	s_barrier
; #define PG8_STAGE(bufoff, gbase, voff) do { _Pragma("unroll") for (int _i = 0; _i < 2; ++_i) \
;         __builtin_amdgcn_global_load_lds((const unsigned*)((const char*)(gbase) + (voff)[_i]), (LAS unsigned*)(lds + (bufoff) + ldsw + _i * 8192), 16, 0, 0); } while (0)
; #define PG8_LDA(dst, b, h) do { _Pragma("unroll") for (int m = 0; m < 4; ++m) _Pragma("unroll") for (int k = 0; k < 2; ++k) dst[m][k] = *(const LAS bf16x8*)(lds + PG8_SA(b, h) + aoff + m * 2048 + k * 1024); } while (0)
; #define PG8_LDB(dst, b, h) do { _Pragma("unroll") for (int n = 0; n < 2; ++n) _Pragma("unroll") for (int k = 0; k < 2; ++k) dst[n][k] = *(const LAS bf16x8*)(lds + PG8_SB(b, h) + boff + n * 2048 + k * 1024); } while (0)
; #define PG8_MMA(ai, bj, At, Bt) do { __builtin_amdgcn_s_setprio(1); _Pragma("unroll") for (int m = 0; m < 4; ++m) _Pragma("unroll") for (int n = 0; n < 2; ++n) _Pragma("unroll") for (int k = 0; k < 2; ++k) \
;         acc[ai][bj][m][n] = __builtin_amdgcn_mfma_f32_16x16x32_bf16(Bt[n][k], At[m][k], acc[ai][bj][m][n], 0, 0, 0); __builtin_amdgcn_s_setprio(0); } while (0)
; #define PG8_WAIT_V(n) asm volatile("s_waitcnt vmcnt(" #n ")" ::: "memory")
; #define PG8_WAIT_L(n) asm volatile("s_waitcnt lgkmcnt(" #n ")" ::: "memory")
; #define PG8_BAR __builtin_amdgcn_s_barrier()
; #define PG8_SCHED __builtin_amdgcn_sched_barrier(0)
; template <class Epi>
; __device__ __forceinline__ void gemm_phase(LAS unsigned char* lds, const Gemm g, const StaticOrder& S, const Epi& E) {
;     ...
;             PG8_WAIT_V(6); PG8_BAR; PG8_MMA(1, 1, At, B1); PG8_BAR;
;             PG8_LDB(B0, 1, 0); PG8_SCHED; PG8_LDA(At, 1, 0); PG8_STAGE(PG8_SA(0, 1), a2 + hstep, voffA);
;             PG8_WAIT_L(8); PG8_BAR; PG8_WAIT_L(0); PG8_MMA(0, 0, At, B0); PG8_BAR; PG8_SCHED;
;             PG8_LDB(B1, 1, 1); PG8_STAGE(PG8_SB(1, 0), b3, voffB);
;             PG8_BAR; PG8_WAIT_L(0); PG8_MMA(0, 1, At, B1); PG8_BAR;
;             PG8_LDA(At, 1, 1); PG8_STAGE(PG8_SA(1, 0), a3, voffA);
;             PG8_BAR; PG8_WAIT_L(0); PG8_MMA(1, 0, At, B0); PG8_BAR; PG8_SCHED;
	v_mfma_f32_16x16x32_bf16 v[52:55], v[176:179], v[144:147], v[52:55]
	v_mfma_f32_16x16x32_bf16 v[52:55], v[180:183], v[148:151], v[52:55]
	v_mfma_f32_16x16x32_bf16 v[36:39], v[176:179], v[152:155], v[36:39]
	v_mfma_f32_16x16x32_bf16 v[36:39], v[180:183], v[156:159], v[36:39]
	v_mfma_f32_16x16x32_bf16 v[20:23], v[176:179], v[160:163], v[20:23]
	v_mfma_f32_16x16x32_bf16 v[20:23], v[180:183], v[164:167], v[20:23]
	v_mfma_f32_16x16x32_bf16 v[4:7], v[176:179], v[168:171], v[4:7]
	v_mfma_f32_16x16x32_bf16 v[4:7], v[180:183], v[172:175], v[4:7]
	v_mfma_f32_16x16x32_bf16 v[0:3], v[204:207], v[168:171], v[0:3]
	v_mfma_f32_16x16x32_bf16 v[0:3], v[218:221], v[172:175], v[0:3]
	v_mfma_f32_16x16x32_bf16 v[12:15], v[204:207], v[160:163], v[12:15]
	v_mfma_f32_16x16x32_bf16 v[12:15], v[218:221], v[164:167], v[12:15]
	v_mfma_f32_16x16x32_bf16 v[32:35], v[204:207], v[152:155], v[32:35]
	v_mfma_f32_16x16x32_bf16 v[32:35], v[218:221], v[156:159], v[32:35]
	v_mfma_f32_16x16x32_bf16 v[48:51], v[204:207], v[144:147], v[48:51]
	v_mfma_f32_16x16x32_bf16 v[48:51], v[218:221], v[148:151], v[48:51]
	s_add_i32 s47, 0, 0x18000
	s_barrier
	ds_read_b128 v[128:131], v247 offset:32768
	ds_read_b128 v[132:135], v247 offset:33792
	ds_read_b128 v[136:139], v247 offset:34816
	ds_read_b128 v[140:143], v247 offset:35840
	s_add_u32 s26, s26, 0x40000
	s_addc_u32 s27, s27, 0
	s_mov_b32 m0, s38
	ds_read_b128 v[144:147], v249 offset:32768
	ds_read_b128 v[148:151], v249 offset:33792
	ds_read_b128 v[152:155], v249 offset:34816
	ds_read_b128 v[156:159], v249 offset:35840
	ds_read_b128 v[160:163], v249 offset:36864
	ds_read_b128 v[164:167], v249 offset:37888
	ds_read_b128 v[168:171], v249 offset:38912
	ds_read_b128 v[172:175], v249 offset:39936
	global_load_lds_dwordx4 v208, s[26:27]
	s_mov_b32 m0, s39
	s_nop 0
	global_load_lds_dwordx4 v210, s[26:27]
	s_waitcnt lgkmcnt(8)
	s_barrier
	s_waitcnt lgkmcnt(0)
	s_waitcnt lgkmcnt(0)
	v_mfma_f32_16x16x32_bf16 v[124:127], v[128:131], v[144:147], v[124:127]
	v_mfma_f32_16x16x32_bf16 v[124:127], v[132:135], v[148:151], v[124:127]
	v_mfma_f32_16x16x32_bf16 v[108:111], v[128:131], v[152:155], v[108:111]
	v_mfma_f32_16x16x32_bf16 v[108:111], v[132:135], v[156:159], v[108:111]
	v_mfma_f32_16x16x32_bf16 v[92:95], v[128:131], v[160:163], v[92:95]
	v_mfma_f32_16x16x32_bf16 v[92:95], v[132:135], v[164:167], v[92:95]
	v_mfma_f32_16x16x32_bf16 v[76:79], v[128:131], v[168:171], v[76:79]
	v_mfma_f32_16x16x32_bf16 v[76:79], v[132:135], v[172:175], v[76:79]
	v_mfma_f32_16x16x32_bf16 v[72:75], v[136:139], v[168:171], v[72:75]
	v_mfma_f32_16x16x32_bf16 v[72:75], v[140:143], v[172:175], v[72:75]
	v_mfma_f32_16x16x32_bf16 v[88:91], v[136:139], v[160:163], v[88:91]
	v_mfma_f32_16x16x32_bf16 v[88:91], v[140:143], v[164:167], v[88:91]
	v_mfma_f32_16x16x32_bf16 v[104:107], v[136:139], v[152:155], v[104:107]
	v_mfma_f32_16x16x32_bf16 v[104:107], v[140:143], v[156:159], v[104:107]
	v_mfma_f32_16x16x32_bf16 v[120:123], v[136:139], v[144:147], v[120:123]
	v_mfma_f32_16x16x32_bf16 v[120:123], v[140:143], v[148:151], v[120:123]
	s_barrier
	s_add_i32 s26, 0, 0x1c000
	s_add_i32 s27, s47, s36
	s_mov_b32 m0, s27
	ds_read_b128 v[176:179], v247 offset:49152
	ds_read_b128 v[180:183], v247 offset:50176
	ds_read_b128 v[204:207], v247 offset:51200
	ds_read_b128 v[218:221], v247 offset:52224
	global_load_lds_dwordx4 v184, s[98:99]
	s_add_i32 m0, s27, 0x2000
	s_nop 0
	global_load_lds_dwordx4 v212, s[98:99]
	s_barrier
	s_waitcnt lgkmcnt(0)
	s_waitcnt lgkmcnt(0)
	v_mfma_f32_16x16x32_bf16 v[116:119], v[176:179], v[144:147], v[116:119]
	v_mfma_f32_16x16x32_bf16 v[116:119], v[180:183], v[148:151], v[116:119]
	v_mfma_f32_16x16x32_bf16 v[100:103], v[176:179], v[152:155], v[100:103]
	v_mfma_f32_16x16x32_bf16 v[100:103], v[180:183], v[156:159], v[100:103]
	v_mfma_f32_16x16x32_bf16 v[84:87], v[176:179], v[160:163], v[84:87]
	v_mfma_f32_16x16x32_bf16 v[84:87], v[180:183], v[164:167], v[84:87]
	v_mfma_f32_16x16x32_bf16 v[68:71], v[176:179], v[168:171], v[68:71]
	v_mfma_f32_16x16x32_bf16 v[68:71], v[180:183], v[172:175], v[68:71]
	v_mfma_f32_16x16x32_bf16 v[64:67], v[204:207], v[168:171], v[64:67]
	v_mfma_f32_16x16x32_bf16 v[64:67], v[218:221], v[172:175], v[64:67]
	v_mfma_f32_16x16x32_bf16 v[80:83], v[204:207], v[160:163], v[80:83]
	v_mfma_f32_16x16x32_bf16 v[80:83], v[218:221], v[164:167], v[80:83]
	v_mfma_f32_16x16x32_bf16 v[96:99], v[204:207], v[152:155], v[96:99]
	v_mfma_f32_16x16x32_bf16 v[96:99], v[218:221], v[156:159], v[96:99]
	v_mfma_f32_16x16x32_bf16 v[112:115], v[204:207], v[144:147], v[112:115]
	v_mfma_f32_16x16x32_bf16 v[112:115], v[218:221], v[148:151], v[112:115]
	s_mov_b32 m0, s41
	s_barrier
; #define PG8_STAGE(bufoff, gbase, voff) do { _Pragma("unroll") for (int _i = 0; _i < 2; ++_i) \
;         __builtin_amdgcn_global_load_lds((const unsigned*)((const char*)(gbase) + (voff)[_i]), (LAS unsigned*)(lds + (bufoff) + ldsw + _i * 8192), 16, 0, 0); } while (0)
; #define PG8_MMA(ai, bj, At, Bt) do { __builtin_amdgcn_s_setprio(1); _Pragma("unroll") for (int m = 0; m < 4; ++m) _Pragma("unroll") for (int n = 0; n < 2; ++n) _Pragma("unroll") for (int k = 0; k < 2; ++k) \
;         acc[ai][bj][m][n] = __builtin_amdgcn_mfma_f32_16x16x32_bf16(Bt[n][k], At[m][k], acc[ai][bj][m][n], 0, 0, 0); __builtin_amdgcn_s_setprio(0); } while (0)
; #define PG8_WAIT_V(n) asm volatile("s_waitcnt vmcnt(" #n ")" ::: "memory")
; #define PG8_WAIT_L(n) asm volatile("s_waitcnt lgkmcnt(" #n ")" ::: "memory")
; #define PG8_BAR __builtin_amdgcn_s_barrier()
; #define PG8_SCHED __builtin_amdgcn_sched_barrier(0)
; template <class Epi>
; __device__ __forceinline__ void gemm_phase(LAS unsigned char* lds, const Gemm g, const StaticOrder& S, const Epi& E) {
;     ...
;             PG8_BAR; PG8_WAIT_L(0); PG8_MMA(1, 0, At, B0); PG8_BAR; PG8_SCHED;
;             PG8_STAGE(PG8_SB(1, 1), b3 + hstep, voffB);
;             PG8_WAIT_V(6); PG8_BAR; PG8_MMA(1, 1, At, B1); PG8_BAR;
;         }
;     __device__ __forceinline__ void operator()(const Acc& acc, const Unit& u, int wr, int wc, int fr, int fq) const {
;         const int row0 = u.pm * 256 + wr * 64 + fr, col0 = u.pn * 256 + wc * 32 + 8 * fq;
;         const bf16_t* __restrict__ gp = gate; bf16_t* __restrict__ mg = merged;
;         u32x4 gw[4][2], pw[2][2];
; #pragma unroll
;         for (int gidx = 0; gidx < 4; ++gidx)
; #pragma unroll
;             for (int bj = 0; bj < 2; ++bj) gw[gidx][bj] = *(const u32x4*)(gp + (size_t)(row0 + gidx * 16) * 4096 + col0 + bj * 128);
; #pragma unroll
;         for (int bj = 0; bj < 2; ++bj) pw[0][bj] = accum ? *(const u32x4*)(mg + (size_t)row0 * 2048 + col0 + bj * 128) : (u32x4){0u, 0u, 0u, 0u};
	ds_read_b128 v[144:147], v249 offset:49152
	ds_read_b128 v[148:151], v249 offset:50176
	ds_read_b128 v[152:155], v249 offset:51200
	ds_read_b128 v[156:159], v249 offset:52224
	ds_read_b128 v[160:163], v249 offset:53248
	ds_read_b128 v[164:167], v249 offset:54272
	ds_read_b128 v[168:171], v249 offset:55296
	ds_read_b128 v[172:175], v249 offset:56320
	global_load_lds_dwordx4 v208, s[100:101]
	s_mov_b32 m0, s42
	s_nop 0
	global_load_lds_dwordx4 v210, s[100:101]
	s_barrier
	s_waitcnt lgkmcnt(0)
	s_waitcnt lgkmcnt(0)
	v_mfma_f32_16x16x32_bf16 v[60:63], v[128:131], v[144:147], v[60:63]
	v_mfma_f32_16x16x32_bf16 v[60:63], v[132:135], v[148:151], v[60:63]
	v_mfma_f32_16x16x32_bf16 v[44:47], v[128:131], v[152:155], v[44:47]
	v_mfma_f32_16x16x32_bf16 v[44:47], v[132:135], v[156:159], v[44:47]
	v_mfma_f32_16x16x32_bf16 v[28:31], v[128:131], v[160:163], v[28:31]
	v_mfma_f32_16x16x32_bf16 v[28:31], v[132:135], v[164:167], v[28:31]
	v_mfma_f32_16x16x32_bf16 v[16:19], v[128:131], v[168:171], v[16:19]
	v_mfma_f32_16x16x32_bf16 v[16:19], v[132:135], v[172:175], v[16:19]
	v_mfma_f32_16x16x32_bf16 v[8:11], v[136:139], v[168:171], v[8:11]
	v_mfma_f32_16x16x32_bf16 v[8:11], v[140:143], v[172:175], v[8:11]
	v_mfma_f32_16x16x32_bf16 v[24:27], v[136:139], v[160:163], v[24:27]
	v_mfma_f32_16x16x32_bf16 v[24:27], v[140:143], v[164:167], v[24:27]
	v_mfma_f32_16x16x32_bf16 v[40:43], v[136:139], v[152:155], v[40:43]
	v_mfma_f32_16x16x32_bf16 v[40:43], v[140:143], v[156:159], v[40:43]
	v_mfma_f32_16x16x32_bf16 v[56:59], v[136:139], v[144:147], v[56:59]
	v_mfma_f32_16x16x32_bf16 v[56:59], v[140:143], v[148:151], v[56:59]
	s_barrier
	s_add_u32 s24, s24, 0x40080
	s_addc_u32 s25, s25, 0
	s_add_i32 s26, s26, s36
	s_mov_b32 m0, s26
	s_nop 0
	global_load_lds_dwordx4 v184, s[24:25]
	s_add_i32 m0, s26, 0x2000
	s_nop 0
	global_load_lds_dwordx4 v212, s[24:25]
	s_waitcnt vmcnt(6)
	s_barrier
	v_mfma_f32_16x16x32_bf16 v[52:55], v[176:179], v[144:147], v[52:55]
	v_mfma_f32_16x16x32_bf16 v[52:55], v[180:183], v[148:151], v[52:55]
	v_mfma_f32_16x16x32_bf16 v[36:39], v[176:179], v[152:155], v[36:39]
	v_mfma_f32_16x16x32_bf16 v[36:39], v[180:183], v[156:159], v[36:39]
	v_mfma_f32_16x16x32_bf16 v[20:23], v[176:179], v[160:163], v[20:23]
	v_mfma_f32_16x16x32_bf16 v[20:23], v[180:183], v[164:167], v[20:23]
	v_mfma_f32_16x16x32_bf16 v[4:7], v[176:179], v[168:171], v[4:7]
	v_mfma_f32_16x16x32_bf16 v[4:7], v[180:183], v[172:175], v[4:7]
	v_mfma_f32_16x16x32_bf16 v[0:3], v[204:207], v[168:171], v[0:3]
	v_mfma_f32_16x16x32_bf16 v[0:3], v[218:221], v[172:175], v[0:3]
	v_mfma_f32_16x16x32_bf16 v[12:15], v[204:207], v[160:163], v[12:15]
	v_mfma_f32_16x16x32_bf16 v[12:15], v[218:221], v[164:167], v[12:15]
	v_mfma_f32_16x16x32_bf16 v[32:35], v[204:207], v[152:155], v[32:35]
	v_mfma_f32_16x16x32_bf16 v[32:35], v[218:221], v[156:159], v[32:35]
	v_mfma_f32_16x16x32_bf16 v[48:51], v[204:207], v[144:147], v[48:51]
	v_mfma_f32_16x16x32_bf16 v[48:51], v[218:221], v[148:151], v[48:51]
	s_add_i32 s46, s46, 2
	s_add_u32 s22, s22, 0x100
	s_addc_u32 s23, s23, 0
	s_add_u32 s43, s43, 0x100
	s_addc_u32 s45, s45, 0
	s_cmp_gt_u32 s46, 13
	s_barrier
	s_cbranch_scc0 .LBB0_43
	v_lshl_or_b32 v128, s8, 8, v248
	v_lshl_add_u32 v222, s20, 8, v187
	v_ashrrev_i32_e32 v129, 31, v128
	v_lshlrev_b64 v[136:137], 1, v[128:129]
	v_ashrrev_i32_e32 v223, 31, v222
	v_lshl_add_u64 v[224:225], s[10:11], 0, v[136:137]
	v_lshlrev_b64 v[130:131], 13, v[222:223]
	v_lshl_add_u64 v[130:131], v[224:225], 0, v[130:131]
	global_load_dwordx4 v[176:179], v[130:131], off
	global_load_dwordx4 v[168:171], v[130:131], off offset:256
	v_or_b32_e32 v130, 16, v222
	v_ashrrev_i32_e32 v131, 31, v130
	v_lshlrev_b64 v[132:133], 13, v[130:131]
	v_or_b32_e32 v230, 32, v222
	v_lshl_add_u64 v[132:133], v[224:225], 0, v[132:133]
	v_ashrrev_i32_e32 v231, 31, v230
	global_load_dwordx4 v[156:159], v[132:133], off
	global_load_dwordx4 v[152:155], v[132:133], off offset:256
	v_lshlrev_b64 v[132:133], 13, v[230:231]
	v_or_b32_e32 v226, 48, v222
	v_lshl_add_u64 v[132:133], v[224:225], 0, v[132:133]
	v_ashrrev_i32_e32 v227, 31, v226
	global_load_dwordx4 v[148:151], v[132:133], off
	global_load_dwordx4 v[144:147], v[132:133], off offset:256
	v_lshlrev_b64 v[132:133], 13, v[226:227]
	v_lshl_add_u64 v[132:133], v[224:225], 0, v[132:133]
	global_load_dwordx4 v[140:143], v[132:133], off
	s_nop 0
	global_load_dwordx4 v[132:135], v[132:133], off offset:256
	v_lshlrev_b64 v[232:233], 12, v[222:223]
	v_lshl_add_u64 v[138:139], s[66:67], 0, v[232:233]
	v_lshl_add_u64 v[136:137], v[138:139], 0, v[136:137]
	v_cndmask_b32_e64 v138, 0, 1, s[0:1]
	v_mov_b32_e32 v172, 0
	v_cmp_ne_u32_e64 s[8:9], 1, v138
	s_andn2_b64 vcc, exec, s[0:1]
	v_mov_b32_e32 v180, 0
	v_mov_b32_e32 v181, 0
	v_mov_b32_e32 v182, 0
	v_mov_b32_e32 v183, 0
	s_cbranch_vccnz .LBB0_46
	global_load_dwordx4 v[180:183], v[136:137], off

; #define PG8_STAGE(bufoff, gbase, voff) do { _Pragma("unroll") for (int _i = 0; _i < 2; ++_i) \
;         __builtin_amdgcn_global_load_lds((const unsigned*)((const char*)(gbase) + (voff)[_i]), (LAS unsigned*)(lds + (bufoff) + ldsw + _i * 8192), 16, 0, 0); } while (0)
; #define PG8_WAIT_V(n) asm volatile("s_waitcnt vmcnt(" #n ")" ::: "memory")
; #define PG8_BAR __builtin_amdgcn_s_barrier()
; template <class Epi>
; __device__ __forceinline__ void gemm_phase(LAS unsigned char* lds, const Gemm g, const StaticOrder& S, const Epi& E) {
;     ...
;     const int aoff = lds_byte(wr * 64 + fr, fq * 8), boff = lds_byte(wc * 32 + fr, fq * 8);
;     ...
;     Unit cur, nxt; int ui = 0;
;     if (!S.next(0, cur)) return;
;     f32x4 acc[2][2][4][2];
; #pragma unroll
;     for (int a = 0; a < 2; ++a)
; #pragma unroll
;         for (int b = 0; b < 2; ++b)
; #pragma unroll
;             for (int m = 0; m < 4; ++m)
; #pragma unroll
;                 for (int n = 0; n < 2; ++n) acc[a][b][m][n] = (f32x4){0.f, 0.f, 0.f, 0.f};
;     bf16x8 At[4][2], B0[2][2], B1[2][2];
;     const char* cA = (const char*)g.A + (size_t)cur.pm * tstep; const char* cB = (const char*)g.Bt + (size_t)cur.pn * tstep;
;     PG8_STAGE(PG8_SB(0, 0), cB, voffB); PG8_STAGE(PG8_SA(0, 0), cA, voffA); PG8_STAGE(PG8_SB(0, 1), cB + hstep, voffB); PG8_STAGE(PG8_SA(0, 1), cA + hstep, voffA);
;     if (wr == 1) PG8_BAR;
;     PG8_WAIT_V(4); PG8_BAR;
;     PG8_STAGE(PG8_SB(1, 0), cB + kstep, voffB); PG8_STAGE(PG8_SA(1, 0), cA + kstep, voffA); PG8_STAGE(PG8_SB(1, 1), cB + hstep + kstep, voffB);
;     PG8_WAIT_V(6); PG8_BAR;
.LBB0_361:
	v_lshrrev_b32_e32 v16, 1, v3
	v_and_b32_e32 v16, 24, v16
	v_and_b32_e32 v7, 15, v3
	v_lshlrev_b32_e32 v17, 1, v16
	v_lshlrev_b32_e32 v3, 2, v3
	v_lshl_or_b32 v142, s0, 6, v7
	v_lshl_or_b32 v7, v7, 6, v17
	s_lshl_b32 s0, s0, 13
	v_and_b32_e32 v3, 32, v3
	v_lshl_add_u64 v[8:9], s[28:29], 0, v[184:185]
	v_mov_b32_e32 v133, v185
	v_bitop3_b32 v17, v7, s0, v3 bitop3:0xde
	s_lshl_b32 s0, s1, 5
	v_lshl_add_u64 v[10:11], s[28:29], 0, v[132:133]
	v_mov_b32_e32 v129, v185
	s_and_b32 s3, s0, 0x60
	s_add_i32 m0, s25, 0x18000
	v_lshl_add_u64 v[8:9], v[8:9], 0, s[58:59]
	v_lshl_add_u64 v[12:13], s[26:27], 0, v[128:129]
	v_mov_b32_e32 v131, v185
	s_lshl_b32 s0, s3, 7
	s_waitcnt vmcnt(4)
	s_barrier
	global_load_lds_dwordx4 v[8:9], off
	v_lshl_add_u64 v[8:9], v[10:11], 0, s[58:59]
	s_add_i32 m0, s25, 0x1a000
	s_add_i32 s42, s25, 0x8000
	s_add_i32 s44, s25, 0xa000
	v_lshl_add_u64 v[14:15], s[26:27], 0, v[130:131]
	v_bitop3_b32 v143, v7, s0, v3 bitop3:0xde
	v_add_u32_e32 v143, 0x10000, v143
	global_load_lds_dwordx4 v[8:9], off
	v_lshl_add_u64 v[8:9], v[12:13], 0, s[58:59]
	s_mov_b32 m0, s42
	s_add_u32 s0, s28, 0x80080
	global_load_lds_dwordx4 v[8:9], off
	v_lshl_add_u64 v[8:9], v[14:15], 0, s[58:59]
	s_mov_b32 m0, s44
	s_addc_u32 s1, s29, 0
	global_load_lds_dwordx4 v[8:9], off
	s_add_i32 m0, s25, 0x1c000
	v_lshl_add_u64 v[8:9], s[0:1], 0, v[184:185]
	global_load_lds_dwordx4 v[8:9], off
	v_lshl_add_u64 v[8:9], s[0:1], 0, v[132:133]
	s_add_i32 m0, s25, 0x1e000
	v_lshlrev_b32_e32 v3, 15, v0
	global_load_lds_dwordx4 v[8:9], off
	v_and_b32_e32 v3, 0xffff0000, v3
	v_lshl_add_u32 v1, v1, 12, v3
	v_and_b32_e32 v0, 1, v0
	v_lshl_or_b32 v0, v0, 6, v1
	v_lshl_add_u32 v134, v2, 1, v0
	v_lshlrev_b32_e32 v0, 15, v4
	v_and_b32_e32 v0, 0xffff0000, v0
	s_waitcnt vmcnt(6)
	v_lshl_add_u32 v0, v5, 12, v0
	v_and_b32_e32 v1, 1, v4
	v_lshl_or_b32 v0, v1, 6, v0
	v_or_b32_e32 v144, s3, v16
	s_ashr_i32 s45, s36, 31
	v_mov_b32_e32 v135, v185
	v_lshl_add_u32 v136, v6, 1, v0
	v_mov_b32_e32 v137, v185
	s_mov_b32 s46, 0
	v_add_u32_e32 v145, 0, v17
	s_barrier
	s_branch .LBB0_363

; #define PG8_STAGE(bufoff, gbase, voff) do { _Pragma("unroll") for (int _i = 0; _i < 2; ++_i) \
;         __builtin_amdgcn_global_load_lds((const unsigned*)((const char*)(gbase) + (voff)[_i]), (LAS unsigned*)(lds + (bufoff) + ldsw + _i * 8192), 16, 0, 0); } while (0)
; #define PG8_LDA(dst, b, h) do { _Pragma("unroll") for (int m = 0; m < 4; ++m) _Pragma("unroll") for (int k = 0; k < 2; ++k) dst[m][k] = *(const LAS bf16x8*)(lds + PG8_SA(b, h) + aoff + m * 2048 + k * 1024); } while (0)
; #define PG8_LDB(dst, b, h) do { _Pragma("unroll") for (int n = 0; n < 2; ++n) _Pragma("unroll") for (int k = 0; k < 2; ++k) dst[n][k] = *(const LAS bf16x8*)(lds + PG8_SB(b, h) + boff + n * 2048 + k * 1024); } while (0)
; #define PG8_MMA(ai, bj, At, Bt) do { __builtin_amdgcn_s_setprio(1); _Pragma("unroll") for (int m = 0; m < 4; ++m) _Pragma("unroll") for (int n = 0; n < 2; ++n) _Pragma("unroll") for (int k = 0; k < 2; ++k) \
;         acc[ai][bj][m][n] = __builtin_amdgcn_mfma_f32_16x16x32_bf16(Bt[n][k], At[m][k], acc[ai][bj][m][n], 0, 0, 0); __builtin_amdgcn_s_setprio(0); } while (0)
; #define PG8_WAIT_V(n) asm volatile("s_waitcnt vmcnt(" #n ")" ::: "memory")
; #define PG8_WAIT_L(n) asm volatile("s_waitcnt lgkmcnt(" #n ")" ::: "memory")
; template <class Epi>
; __device__ __forceinline__ void gemm_phase(LAS unsigned char* lds, const Gemm g, const StaticOrder& S, const Epi& E) {
;     ...
;         for (int t = 0; t < nt; t += 2) {
;             const bool last = (t == nt - 2);
;             const char* a1 = cA + (size_t)(t + 1) * kstep;
;             const char* a2 = last ? nA : cA + (size_t)(t + 2) * kstep; const char* b2 = last ? nB : cB + (size_t)(t + 2) * kstep;
;             const char* a3 = a2 + kstep; const char* b3 = b2 + kstep;
;             PG8_LDB(B0, 0, 0); PG8_SCHED; PG8_LDA(At, 0, 0); PG8_STAGE(PG8_SA(1, 1), a1 + hstep, voffA);
;             PG8_WAIT_L(8); PG8_BAR; PG8_WAIT_L(0); PG8_MMA(0, 0, At, B0); PG8_BAR; PG8_SCHED;
;             PG8_LDB(B1, 0, 1); PG8_STAGE(PG8_SB(0, 0), b2, voffB);
;             PG8_BAR; PG8_WAIT_L(0); PG8_MMA(0, 1, At, B1); PG8_BAR;
;             PG8_LDA(At, 0, 1); PG8_STAGE(PG8_SA(0, 0), a2, voffA);
;             PG8_BAR; PG8_WAIT_L(0); PG8_MMA(1, 0, At, B0); PG8_BAR; PG8_SCHED;
;             PG8_STAGE(PG8_SB(0, 1), b2 + hstep, voffB);
;             PG8_WAIT_V(6); PG8_BAR; PG8_MMA(1, 1, At, B1); PG8_BAR;
.LBB0_366:
	s_add_u32 s28, s26, 0xfff80080
	s_addc_u32 s29, s27, -1
	s_add_i32 s47, 0, 0x10000
	ds_read_b128 v[138:141], v143
	ds_read_b128 v[146:149], v143 offset:1024
	ds_read_b128 v[150:153], v143 offset:2048
	ds_read_b128 v[154:157], v143 offset:3072
	s_cmp_eq_u32 s43, 28
	s_cselect_b32 s31, s3, s29
	s_cselect_b32 s30, s9, s28
	s_cselect_b32 s29, s1, s35
	s_cselect_b32 s28, s19, s34
	s_add_i32 m0, s25, 0xc000
	ds_read_b128 v[158:161], v145
	ds_read_b128 v[162:165], v145 offset:1024
	ds_read_b128 v[166:169], v145 offset:2048
	ds_read_b128 v[170:173], v145 offset:3072
	ds_read_b128 v[174:177], v145 offset:4096
	ds_read_b128 v[178:181], v145 offset:5120
	ds_read_b128 v[204:207], v145 offset:6144
	ds_read_b128 v[208:211], v145 offset:7168
	global_load_lds_dwordx4 v134, s[26:27]
	s_add_i32 m0, s25, 0xe000
	s_nop 0
	global_load_lds_dwordx4 v136, s[26:27]
	s_waitcnt lgkmcnt(8)
	s_barrier
	s_waitcnt lgkmcnt(0)
	s_waitcnt lgkmcnt(0)
	v_mfma_f32_16x16x32_bf16 v[124:127], v[138:141], v[158:161], v[124:127]
	v_mfma_f32_16x16x32_bf16 v[124:127], v[146:149], v[162:165], v[124:127]
	v_mfma_f32_16x16x32_bf16 v[108:111], v[138:141], v[166:169], v[108:111]
	v_mfma_f32_16x16x32_bf16 v[108:111], v[146:149], v[170:173], v[108:111]
	v_mfma_f32_16x16x32_bf16 v[92:95], v[138:141], v[174:177], v[92:95]
	v_mfma_f32_16x16x32_bf16 v[92:95], v[146:149], v[178:181], v[92:95]
	v_mfma_f32_16x16x32_bf16 v[76:79], v[138:141], v[204:207], v[76:79]
	v_mfma_f32_16x16x32_bf16 v[76:79], v[146:149], v[208:211], v[76:79]
	v_mfma_f32_16x16x32_bf16 v[72:75], v[150:153], v[204:207], v[72:75]
	v_mfma_f32_16x16x32_bf16 v[72:75], v[154:157], v[208:211], v[72:75]
	v_mfma_f32_16x16x32_bf16 v[88:91], v[150:153], v[174:177], v[88:91]
	v_mfma_f32_16x16x32_bf16 v[88:91], v[154:157], v[178:181], v[88:91]
	v_mfma_f32_16x16x32_bf16 v[104:107], v[150:153], v[166:169], v[104:107]
	v_mfma_f32_16x16x32_bf16 v[104:107], v[154:157], v[170:173], v[104:107]
	v_mfma_f32_16x16x32_bf16 v[120:123], v[150:153], v[158:161], v[120:123]
	v_mfma_f32_16x16x32_bf16 v[120:123], v[154:157], v[162:165], v[120:123]
	s_barrier
	s_add_i32 s52, 0, 0x14000
	s_add_i32 s47, s47, s38
	ds_read_b128 v[212:215], v143 offset:16384
	ds_read_b128 v[216:219], v143 offset:17408
	ds_read_b128 v[220:223], v143 offset:18432
	ds_read_b128 v[224:227], v143 offset:19456
	s_mov_b32 m0, s47
	s_add_u32 s98, s28, s58
	s_addc_u32 s99, s29, s59
	global_load_lds_dwordx4 v184, s[28:29]
	s_add_i32 m0, s47, 0x2000
	s_nop 0
	global_load_lds_dwordx4 v132, s[28:29]
	s_barrier
	s_waitcnt lgkmcnt(0)
	s_waitcnt lgkmcnt(0)
	v_mfma_f32_16x16x32_bf16 v[116:119], v[212:215], v[158:161], v[116:119]
	v_mfma_f32_16x16x32_bf16 v[116:119], v[216:219], v[162:165], v[116:119]
	v_mfma_f32_16x16x32_bf16 v[100:103], v[212:215], v[166:169], v[100:103]
	v_mfma_f32_16x16x32_bf16 v[100:103], v[216:219], v[170:173], v[100:103]
	v_mfma_f32_16x16x32_bf16 v[84:87], v[212:215], v[174:177], v[84:87]
	v_mfma_f32_16x16x32_bf16 v[84:87], v[216:219], v[178:181], v[84:87]
	v_mfma_f32_16x16x32_bf16 v[68:71], v[212:215], v[204:207], v[68:71]
	v_mfma_f32_16x16x32_bf16 v[68:71], v[216:219], v[208:211], v[68:71]
	v_mfma_f32_16x16x32_bf16 v[64:67], v[220:223], v[204:207], v[64:67]
	v_mfma_f32_16x16x32_bf16 v[64:67], v[224:227], v[208:211], v[64:67]
	v_mfma_f32_16x16x32_bf16 v[80:83], v[220:223], v[174:177], v[80:83]
	v_mfma_f32_16x16x32_bf16 v[80:83], v[224:227], v[178:181], v[80:83]
	v_mfma_f32_16x16x32_bf16 v[96:99], v[220:223], v[166:169], v[96:99]
	v_mfma_f32_16x16x32_bf16 v[96:99], v[224:227], v[170:173], v[96:99]
	v_mfma_f32_16x16x32_bf16 v[112:115], v[220:223], v[158:161], v[112:115]
	v_mfma_f32_16x16x32_bf16 v[112:115], v[224:227], v[162:165], v[112:115]
	s_mov_b32 m0, s25
	s_barrier
	ds_read_b128 v[158:161], v145 offset:16384
	ds_read_b128 v[162:165], v145 offset:17408
	ds_read_b128 v[166:169], v145 offset:18432
	ds_read_b128 v[170:173], v145 offset:19456
	ds_read_b128 v[174:177], v145 offset:20480
	ds_read_b128 v[178:181], v145 offset:21504
	ds_read_b128 v[204:207], v145 offset:22528
	ds_read_b128 v[208:211], v145 offset:23552
	global_load_lds_dwordx4 v128, s[30:31]
	s_add_u32 s100, s30, s58
	s_addc_u32 s101, s31, s59
	s_mov_b32 m0, s39
	s_nop 0
	global_load_lds_dwordx4 v130, s[30:31]
	s_barrier
	s_waitcnt lgkmcnt(0)
	s_waitcnt lgkmcnt(0)
	v_mfma_f32_16x16x32_bf16 v[60:63], v[138:141], v[158:161], v[60:63]
	v_mfma_f32_16x16x32_bf16 v[60:63], v[146:149], v[162:165], v[60:63]
	v_mfma_f32_16x16x32_bf16 v[44:47], v[138:141], v[166:169], v[44:47]
	v_mfma_f32_16x16x32_bf16 v[44:47], v[146:149], v[170:173], v[44:47]
	v_mfma_f32_16x16x32_bf16 v[28:31], v[138:141], v[174:177], v[28:31]
	v_mfma_f32_16x16x32_bf16 v[28:31], v[146:149], v[178:181], v[28:31]
	v_mfma_f32_16x16x32_bf16 v[12:15], v[138:141], v[204:207], v[12:15]
	v_mfma_f32_16x16x32_bf16 v[12:15], v[146:149], v[208:211], v[12:15]
	v_mfma_f32_16x16x32_bf16 v[8:11], v[150:153], v[204:207], v[8:11]
	v_mfma_f32_16x16x32_bf16 v[8:11], v[154:157], v[208:211], v[8:11]
	v_mfma_f32_16x16x32_bf16 v[24:27], v[150:153], v[174:177], v[24:27]
	v_mfma_f32_16x16x32_bf16 v[24:27], v[154:157], v[178:181], v[24:27]
	v_mfma_f32_16x16x32_bf16 v[40:43], v[150:153], v[166:169], v[40:43]
	v_mfma_f32_16x16x32_bf16 v[40:43], v[154:157], v[170:173], v[40:43]
	v_mfma_f32_16x16x32_bf16 v[56:59], v[150:153], v[158:161], v[56:59]
	v_mfma_f32_16x16x32_bf16 v[56:59], v[154:157], v[162:165], v[56:59]
	s_barrier
	s_add_u32 s50, s28, 0x80000
	s_addc_u32 s51, s29, 0
	s_add_i32 s47, s52, s38
	s_mov_b32 m0, s47
	s_nop 0
	global_load_lds_dwordx4 v184, s[50:51]
	s_add_i32 m0, s47, 0x2000
	s_nop 0
	global_load_lds_dwordx4 v132, s[50:51]
	s_waitcnt vmcnt(6)
	s_barrier
; #define PG8_STAGE(bufoff, gbase, voff) do { _Pragma("unroll") for (int _i = 0; _i < 2; ++_i) \
;         __builtin_amdgcn_global_load_lds((const unsigned*)((const char*)(gbase) + (voff)[_i]), (LAS unsigned*)(lds + (bufoff) + ldsw + _i * 8192), 16, 0, 0); } while (0)
; #define PG8_LDA(dst, b, h) do { _Pragma("unroll") for (int m = 0; m < 4; ++m) _Pragma("unroll") for (int k = 0; k < 2; ++k) dst[m][k] = *(const LAS bf16x8*)(lds + PG8_SA(b, h) + aoff + m * 2048 + k * 1024); } while (0)
; #define PG8_LDB(dst, b, h) do { _Pragma("unroll") for (int n = 0; n < 2; ++n) _Pragma("unroll") for (int k = 0; k < 2; ++k) dst[n][k] = *(const LAS bf16x8*)(lds + PG8_SB(b, h) + boff + n * 2048 + k * 1024); } while (0)
; #define PG8_MMA(ai, bj, At, Bt) do { __builtin_amdgcn_s_setprio(1); _Pragma("unroll") for (int m = 0; m < 4; ++m) _Pragma("unroll") for (int n = 0; n < 2; ++n) _Pragma("unroll") for (int k = 0; k < 2; ++k) \
;         acc[ai][bj][m][n] = __builtin_amdgcn_mfma_f32_16x16x32_bf16(Bt[n][k], At[m][k], acc[ai][bj][m][n], 0, 0, 0); __builtin_amdgcn_s_setprio(0); } while (0)
; #define PG8_WAIT_V(n) asm volatile("s_waitcnt vmcnt(" #n ")" ::: "memory")
; #define PG8_WAIT_L(n) asm volatile("s_waitcnt lgkmcnt(" #n ")" ::: "memory")
; #define PG8_BAR __builtin_amdgcn_s_barrier()
; #define PG8_SCHED __builtin_amdgcn_sched_barrier(0)
; template <class Epi>
; __device__ __forceinline__ void gemm_phase(LAS unsigned char* lds, const Gemm g, const StaticOrder& S, const Epi& E) {
;     ...
;             PG8_WAIT_V(6); PG8_BAR; PG8_MMA(1, 1, At, B1); PG8_BAR;
;             PG8_LDB(B0, 1, 0); PG8_SCHED; PG8_LDA(At, 1, 0); PG8_STAGE(PG8_SA(0, 1), a2 + hstep, voffA);
;             PG8_WAIT_L(8); PG8_BAR; PG8_WAIT_L(0); PG8_MMA(0, 0, At, B0); PG8_BAR; PG8_SCHED;
;             PG8_LDB(B1, 1, 1); PG8_STAGE(PG8_SB(1, 0), b3, voffB);
;             PG8_BAR; PG8_WAIT_L(0); PG8_MMA(0, 1, At, B1); PG8_BAR;
;             PG8_LDA(At, 1, 1); PG8_STAGE(PG8_SA(1, 0), a3, voffA);
;             PG8_BAR; PG8_WAIT_L(0); PG8_MMA(1, 0, At, B0); PG8_BAR; PG8_SCHED;
	v_mfma_f32_16x16x32_bf16 v[52:55], v[212:215], v[158:161], v[52:55]
	v_mfma_f32_16x16x32_bf16 v[52:55], v[216:219], v[162:165], v[52:55]
	v_mfma_f32_16x16x32_bf16 v[36:39], v[212:215], v[166:169], v[36:39]
	v_mfma_f32_16x16x32_bf16 v[36:39], v[216:219], v[170:173], v[36:39]
	v_mfma_f32_16x16x32_bf16 v[20:23], v[212:215], v[174:177], v[20:23]
	v_mfma_f32_16x16x32_bf16 v[20:23], v[216:219], v[178:181], v[20:23]
	v_mfma_f32_16x16x32_bf16 v[4:7], v[212:215], v[204:207], v[4:7]
	v_mfma_f32_16x16x32_bf16 v[4:7], v[216:219], v[208:211], v[4:7]
	v_mfma_f32_16x16x32_bf16 v[0:3], v[220:223], v[204:207], v[0:3]
	v_mfma_f32_16x16x32_bf16 v[0:3], v[224:227], v[208:211], v[0:3]
	v_mfma_f32_16x16x32_bf16 v[16:19], v[220:223], v[174:177], v[16:19]
	v_mfma_f32_16x16x32_bf16 v[16:19], v[224:227], v[178:181], v[16:19]
	v_mfma_f32_16x16x32_bf16 v[32:35], v[220:223], v[166:169], v[32:35]
	v_mfma_f32_16x16x32_bf16 v[32:35], v[224:227], v[170:173], v[32:35]
	v_mfma_f32_16x16x32_bf16 v[48:51], v[220:223], v[158:161], v[48:51]
	v_mfma_f32_16x16x32_bf16 v[48:51], v[224:227], v[162:165], v[48:51]
	s_add_i32 s47, 0, 0x18000
	s_barrier
	ds_read_b128 v[138:141], v143 offset:32768
	ds_read_b128 v[146:149], v143 offset:33792
	ds_read_b128 v[150:153], v143 offset:34816
	ds_read_b128 v[154:157], v143 offset:35840
	s_add_u32 s30, s30, 0x80000
	s_addc_u32 s31, s31, 0
	s_mov_b32 m0, s40
	ds_read_b128 v[158:161], v145 offset:32768
	ds_read_b128 v[162:165], v145 offset:33792
	ds_read_b128 v[166:169], v145 offset:34816
	ds_read_b128 v[170:173], v145 offset:35840
	ds_read_b128 v[174:177], v145 offset:36864
	ds_read_b128 v[178:181], v145 offset:37888
	ds_read_b128 v[204:207], v145 offset:38912
	ds_read_b128 v[208:211], v145 offset:39936
	global_load_lds_dwordx4 v128, s[30:31]
	s_mov_b32 m0, s41
	s_nop 0
	global_load_lds_dwordx4 v130, s[30:31]
	s_waitcnt lgkmcnt(8)
	s_barrier
	s_waitcnt lgkmcnt(0)
	s_waitcnt lgkmcnt(0)
	v_mfma_f32_16x16x32_bf16 v[124:127], v[138:141], v[158:161], v[124:127]
	v_mfma_f32_16x16x32_bf16 v[124:127], v[146:149], v[162:165], v[124:127]
	v_mfma_f32_16x16x32_bf16 v[108:111], v[138:141], v[166:169], v[108:111]
	v_mfma_f32_16x16x32_bf16 v[108:111], v[146:149], v[170:173], v[108:111]
	v_mfma_f32_16x16x32_bf16 v[92:95], v[138:141], v[174:177], v[92:95]
	v_mfma_f32_16x16x32_bf16 v[92:95], v[146:149], v[178:181], v[92:95]
	v_mfma_f32_16x16x32_bf16 v[76:79], v[138:141], v[204:207], v[76:79]
	v_mfma_f32_16x16x32_bf16 v[76:79], v[146:149], v[208:211], v[76:79]
	v_mfma_f32_16x16x32_bf16 v[72:75], v[150:153], v[204:207], v[72:75]
	v_mfma_f32_16x16x32_bf16 v[72:75], v[154:157], v[208:211], v[72:75]
	v_mfma_f32_16x16x32_bf16 v[88:91], v[150:153], v[174:177], v[88:91]
	v_mfma_f32_16x16x32_bf16 v[88:91], v[154:157], v[178:181], v[88:91]
	v_mfma_f32_16x16x32_bf16 v[104:107], v[150:153], v[166:169], v[104:107]
	v_mfma_f32_16x16x32_bf16 v[104:107], v[154:157], v[170:173], v[104:107]
	v_mfma_f32_16x16x32_bf16 v[120:123], v[150:153], v[158:161], v[120:123]
	v_mfma_f32_16x16x32_bf16 v[120:123], v[154:157], v[162:165], v[120:123]
	s_barrier
	s_add_i32 s30, 0, 0x1c000
	s_add_i32 s31, s47, s38
	s_mov_b32 m0, s31
	ds_read_b128 v[212:215], v143 offset:49152
	ds_read_b128 v[216:219], v143 offset:50176
	ds_read_b128 v[220:223], v143 offset:51200
	ds_read_b128 v[224:227], v143 offset:52224
	global_load_lds_dwordx4 v184, s[98:99]
	s_add_i32 m0, s31, 0x2000
	s_nop 0
	global_load_lds_dwordx4 v132, s[98:99]
	s_barrier
	s_waitcnt lgkmcnt(0)
	s_waitcnt lgkmcnt(0)
	v_mfma_f32_16x16x32_bf16 v[116:119], v[212:215], v[158:161], v[116:119]
	v_mfma_f32_16x16x32_bf16 v[116:119], v[216:219], v[162:165], v[116:119]
	v_mfma_f32_16x16x32_bf16 v[100:103], v[212:215], v[166:169], v[100:103]
	v_mfma_f32_16x16x32_bf16 v[100:103], v[216:219], v[170:173], v[100:103]
	v_mfma_f32_16x16x32_bf16 v[84:87], v[212:215], v[174:177], v[84:87]
	v_mfma_f32_16x16x32_bf16 v[84:87], v[216:219], v[178:181], v[84:87]
	v_mfma_f32_16x16x32_bf16 v[68:71], v[212:215], v[204:207], v[68:71]
	v_mfma_f32_16x16x32_bf16 v[68:71], v[216:219], v[208:211], v[68:71]
	v_mfma_f32_16x16x32_bf16 v[64:67], v[220:223], v[204:207], v[64:67]
	v_mfma_f32_16x16x32_bf16 v[64:67], v[224:227], v[208:211], v[64:67]
	v_mfma_f32_16x16x32_bf16 v[80:83], v[220:223], v[174:177], v[80:83]
	v_mfma_f32_16x16x32_bf16 v[80:83], v[224:227], v[178:181], v[80:83]
	v_mfma_f32_16x16x32_bf16 v[96:99], v[220:223], v[166:169], v[96:99]
	v_mfma_f32_16x16x32_bf16 v[96:99], v[224:227], v[170:173], v[96:99]
	v_mfma_f32_16x16x32_bf16 v[112:115], v[220:223], v[158:161], v[112:115]
	v_mfma_f32_16x16x32_bf16 v[112:115], v[224:227], v[162:165], v[112:115]
	s_mov_b32 m0, s42
	s_barrier
; #define PG8_STAGE(bufoff, gbase, voff) do { _Pragma("unroll") for (int _i = 0; _i < 2; ++_i) \
;         __builtin_amdgcn_global_load_lds((const unsigned*)((const char*)(gbase) + (voff)[_i]), (LAS unsigned*)(lds + (bufoff) + ldsw + _i * 8192), 16, 0, 0); } while (0)
; #define PG8_MMA(ai, bj, At, Bt) do { __builtin_amdgcn_s_setprio(1); _Pragma("unroll") for (int m = 0; m < 4; ++m) _Pragma("unroll") for (int n = 0; n < 2; ++n) _Pragma("unroll") for (int k = 0; k < 2; ++k) \
;         acc[ai][bj][m][n] = __builtin_amdgcn_mfma_f32_16x16x32_bf16(Bt[n][k], At[m][k], acc[ai][bj][m][n], 0, 0, 0); __builtin_amdgcn_s_setprio(0); } while (0)
; #define PG8_WAIT_V(n) asm volatile("s_waitcnt vmcnt(" #n ")" ::: "memory")
; #define PG8_WAIT_L(n) asm volatile("s_waitcnt lgkmcnt(" #n ")" ::: "memory")
; #define PG8_BAR __builtin_amdgcn_s_barrier()
; #define PG8_SCHED __builtin_amdgcn_sched_barrier(0)
; template <class Epi>
; __device__ __forceinline__ void gemm_phase(LAS unsigned char* lds, const Gemm g, const StaticOrder& S, const Epi& E) {
;     ...
;             PG8_BAR; PG8_WAIT_L(0); PG8_MMA(1, 0, At, B0); PG8_BAR; PG8_SCHED;
;             PG8_STAGE(PG8_SB(1, 1), b3 + hstep, voffB);
;             PG8_WAIT_V(6); PG8_BAR; PG8_MMA(1, 1, At, B1); PG8_BAR;
;         }
;     __device__ __forceinline__ void operator()(const Acc& acc, const Unit& u, int wr, int wc, int fr, int fq) const {
;         const int pn = u.pn; const int row0 = u.pm * 256 + wr * 64 + fr;
;         bf16_t* base; int ld, cb; bool act;
;         if (vt) { base = vt; ld = TH; cb = 256 * pn; act = false; }
;         else if (gmode) { base = g; ld = 4096; cb = 256 * pn; act = true; }
;         else if (pn < 8) { base = zna; ld = 2048; cb = 256 * pn; act = false; }
;         else if (pn < 16) { base = zqk; ld = 2048; cb = 256 * (pn - 8); act = false; }
;         else if (pn < 24) { base = vo; ld = 2048; cb = 256 * (pn - 16); act = pn >= 20; }
;         else { base = g; ld = 4096; cb = 256 * (pn - 24); act = true; }
	ds_read_b128 v[158:161], v145 offset:49152
	ds_read_b128 v[162:165], v145 offset:50176
	ds_read_b128 v[166:169], v145 offset:51200
	ds_read_b128 v[170:173], v145 offset:52224
	ds_read_b128 v[174:177], v145 offset:53248
	ds_read_b128 v[178:181], v145 offset:54272
	ds_read_b128 v[204:207], v145 offset:55296
	ds_read_b128 v[208:211], v145 offset:56320
	global_load_lds_dwordx4 v128, s[100:101]
	s_mov_b32 m0, s44
	s_nop 0
	global_load_lds_dwordx4 v130, s[100:101]
	s_barrier
	s_waitcnt lgkmcnt(0)
	s_waitcnt lgkmcnt(0)
	v_mfma_f32_16x16x32_bf16 v[60:63], v[138:141], v[158:161], v[60:63]
	v_mfma_f32_16x16x32_bf16 v[60:63], v[146:149], v[162:165], v[60:63]
	v_mfma_f32_16x16x32_bf16 v[44:47], v[138:141], v[166:169], v[44:47]
	v_mfma_f32_16x16x32_bf16 v[44:47], v[146:149], v[170:173], v[44:47]
	v_mfma_f32_16x16x32_bf16 v[28:31], v[138:141], v[174:177], v[28:31]
	v_mfma_f32_16x16x32_bf16 v[28:31], v[146:149], v[178:181], v[28:31]
	v_mfma_f32_16x16x32_bf16 v[12:15], v[138:141], v[204:207], v[12:15]
	v_mfma_f32_16x16x32_bf16 v[12:15], v[146:149], v[208:211], v[12:15]
	v_mfma_f32_16x16x32_bf16 v[8:11], v[150:153], v[204:207], v[8:11]
	v_mfma_f32_16x16x32_bf16 v[8:11], v[154:157], v[208:211], v[8:11]
	v_mfma_f32_16x16x32_bf16 v[24:27], v[150:153], v[174:177], v[24:27]
	v_mfma_f32_16x16x32_bf16 v[24:27], v[154:157], v[178:181], v[24:27]
	v_mfma_f32_16x16x32_bf16 v[40:43], v[150:153], v[166:169], v[40:43]
	v_mfma_f32_16x16x32_bf16 v[40:43], v[154:157], v[170:173], v[40:43]
	v_mfma_f32_16x16x32_bf16 v[56:59], v[150:153], v[158:161], v[56:59]
	v_mfma_f32_16x16x32_bf16 v[56:59], v[154:157], v[162:165], v[56:59]
	s_barrier
	s_add_u32 s28, s28, 0x80080
	s_addc_u32 s29, s29, 0
	s_add_i32 s30, s30, s38
	s_mov_b32 m0, s30
	s_nop 0
	global_load_lds_dwordx4 v184, s[28:29]
	s_add_i32 m0, s30, 0x2000
	s_nop 0
	global_load_lds_dwordx4 v132, s[28:29]
	s_waitcnt vmcnt(6)
	s_barrier
	v_mfma_f32_16x16x32_bf16 v[52:55], v[212:215], v[158:161], v[52:55]
	v_mfma_f32_16x16x32_bf16 v[52:55], v[216:219], v[162:165], v[52:55]
	v_mfma_f32_16x16x32_bf16 v[36:39], v[212:215], v[166:169], v[36:39]
	v_mfma_f32_16x16x32_bf16 v[36:39], v[216:219], v[170:173], v[36:39]
	v_mfma_f32_16x16x32_bf16 v[20:23], v[212:215], v[174:177], v[20:23]
	v_mfma_f32_16x16x32_bf16 v[20:23], v[216:219], v[178:181], v[20:23]
	v_mfma_f32_16x16x32_bf16 v[4:7], v[212:215], v[204:207], v[4:7]
	v_mfma_f32_16x16x32_bf16 v[4:7], v[216:219], v[208:211], v[4:7]
	v_mfma_f32_16x16x32_bf16 v[0:3], v[220:223], v[204:207], v[0:3]
	v_mfma_f32_16x16x32_bf16 v[0:3], v[224:227], v[208:211], v[0:3]
	v_mfma_f32_16x16x32_bf16 v[16:19], v[220:223], v[174:177], v[16:19]
	v_mfma_f32_16x16x32_bf16 v[16:19], v[224:227], v[178:181], v[16:19]
	v_mfma_f32_16x16x32_bf16 v[32:35], v[220:223], v[166:169], v[32:35]
	v_mfma_f32_16x16x32_bf16 v[32:35], v[224:227], v[170:173], v[32:35]
	v_mfma_f32_16x16x32_bf16 v[48:51], v[220:223], v[158:161], v[48:51]
	v_mfma_f32_16x16x32_bf16 v[48:51], v[224:227], v[162:165], v[48:51]
	s_add_i32 s43, s43, 2
	s_add_u32 s26, s26, 0x100
	s_addc_u32 s27, s27, 0
	s_add_u32 s34, s34, 0x100
	s_addc_u32 s35, s35, 0
	s_cmp_gt_u32 s43, 29
	s_barrier
	s_cbranch_scc0 .LBB0_366
	s_andn2_b64 vcc, exec, s[16:17]
	s_lshl_b32 s1, s8, 8
	s_cbranch_vccnz .LBB0_378
	s_cmp_lt_i32 s8, 8
	s_cbranch_scc1 .LBB0_410
	s_cmp_gt_u32 s8, 15
	s_mov_b64 s[34:35], -1
	s_cbranch_scc0 .LBB0_375
	s_mov_b64 s[30:31], -1
	s_cmp_gt_u32 s8, 23
	s_mov_b64 s[28:29], -1
	s_cbranch_scc0 .LBB0_372
	s_add_i32 s3, s1, 0xffffe800
	s_mov_b64 s[28:29], 0

; #define PG8_STAGE(bufoff, gbase, voff) do { _Pragma("unroll") for (int _i = 0; _i < 2; ++_i) \
;         __builtin_amdgcn_global_load_lds((const unsigned*)((const char*)(gbase) + (voff)[_i]), (LAS unsigned*)(lds + (bufoff) + ldsw + _i * 8192), 16, 0, 0); } while (0)
; #define PG8_WAIT_V(n) asm volatile("s_waitcnt vmcnt(" #n ")" ::: "memory")
; #define PG8_BAR __builtin_amdgcn_s_barrier()
; template <class Epi>
; __device__ __forceinline__ void gemm_phase(LAS unsigned char* lds, const Gemm g, const StaticOrder& S, const Epi& E) {
;     ...
;     const int aoff = lds_byte(wr * 64 + fr, fq * 8), boff = lds_byte(wc * 32 + fr, fq * 8);
;     ...
;     Unit cur, nxt; int ui = 0;
;     if (!S.next(0, cur)) return;
;     f32x4 acc[2][2][4][2];
; #pragma unroll
;     for (int a = 0; a < 2; ++a)
; #pragma unroll
;         for (int b = 0; b < 2; ++b)
; #pragma unroll
;             for (int m = 0; m < 4; ++m)
; #pragma unroll
;                 for (int n = 0; n < 2; ++n) acc[a][b][m][n] = (f32x4){0.f, 0.f, 0.f, 0.f};
;     bf16x8 At[4][2], B0[2][2], B1[2][2];
;     const char* cA = (const char*)g.A + (size_t)cur.pm * tstep; const char* cB = (const char*)g.Bt + (size_t)cur.pn * tstep;
;     PG8_STAGE(PG8_SB(0, 0), cB, voffB); PG8_STAGE(PG8_SA(0, 0), cA, voffA); PG8_STAGE(PG8_SB(0, 1), cB + hstep, voffB); PG8_STAGE(PG8_SA(0, 1), cA + hstep, voffA);
;     if (wr == 1) PG8_BAR;
;     PG8_WAIT_V(4); PG8_BAR;
;     PG8_STAGE(PG8_SB(1, 0), cB + kstep, voffB); PG8_STAGE(PG8_SA(1, 0), cA + kstep, voffA); PG8_STAGE(PG8_SB(1, 1), cB + hstep + kstep, voffB);
;     PG8_WAIT_V(6); PG8_BAR;
.LBB0_428:
	v_lshrrev_b32_e32 v16, 1, v5
	v_and_b32_e32 v16, 24, v16
	v_and_b32_e32 v7, 15, v5
	v_lshlrev_b32_e32 v17, 1, v16
	v_lshlrev_b32_e32 v5, 2, v5
	v_lshl_or_b32 v142, s0, 6, v7
	v_lshl_or_b32 v7, v7, 6, v17
	s_lshl_b32 s0, s0, 13
	v_and_b32_e32 v5, 32, v5
	v_lshl_add_u64 v[8:9], s[28:29], 0, v[184:185]
	v_mov_b32_e32 v133, v185
	v_bitop3_b32 v17, v7, s0, v5 bitop3:0xde
	s_lshl_b32 s0, s1, 5
	v_lshl_add_u64 v[10:11], s[28:29], 0, v[132:133]
	v_mov_b32_e32 v129, v185
	s_and_b32 s3, s0, 0x60
	s_add_i32 m0, s25, 0x18000
	v_lshl_add_u64 v[8:9], v[8:9], 0, s[58:59]
	v_lshl_add_u64 v[12:13], s[26:27], 0, v[128:129]
	v_mov_b32_e32 v131, v185
	s_lshl_b32 s0, s3, 7
	s_waitcnt vmcnt(4)
	s_barrier
	global_load_lds_dwordx4 v[8:9], off
	v_lshl_add_u64 v[8:9], v[10:11], 0, s[58:59]
	s_add_i32 m0, s25, 0x1a000
	s_add_i32 s42, s25, 0x8000
	s_add_i32 s44, s25, 0xa000
	v_lshl_add_u64 v[14:15], s[26:27], 0, v[130:131]
	v_bitop3_b32 v143, v7, s0, v5 bitop3:0xde
	v_add_u32_e32 v143, 0x10000, v143
	global_load_lds_dwordx4 v[8:9], off
	v_lshl_add_u64 v[8:9], v[12:13], 0, s[58:59]
	s_mov_b32 m0, s42
	s_add_u32 s0, s28, 0x80080
	global_load_lds_dwordx4 v[8:9], off
	v_lshl_add_u64 v[8:9], v[14:15], 0, s[58:59]
	s_mov_b32 m0, s44
	s_addc_u32 s1, s29, 0
	global_load_lds_dwordx4 v[8:9], off
	s_add_i32 m0, s25, 0x1c000
	v_lshl_add_u64 v[8:9], s[0:1], 0, v[184:185]
	global_load_lds_dwordx4 v[8:9], off
	v_lshl_add_u64 v[8:9], s[0:1], 0, v[132:133]
	s_add_i32 m0, s25, 0x1e000
	v_lshlrev_b32_e32 v5, 15, v0
	global_load_lds_dwordx4 v[8:9], off
	v_and_b32_e32 v5, 0xffff0000, v5
	v_lshl_add_u32 v1, v1, 12, v5
	v_and_b32_e32 v0, 1, v0
	v_lshl_or_b32 v0, v0, 6, v1
	v_lshl_add_u32 v134, v2, 1, v0
	v_lshlrev_b32_e32 v0, 15, v3
	v_and_b32_e32 v0, 0xffff0000, v0
	s_waitcnt vmcnt(6)
	v_lshl_add_u32 v0, v4, 12, v0
	v_and_b32_e32 v1, 1, v3
	v_lshl_or_b32 v0, v1, 6, v0
	v_or_b32_e32 v144, s3, v16
	s_ashr_i32 s45, s36, 31
	v_mov_b32_e32 v135, v185
	v_lshl_add_u32 v136, v6, 1, v0
	v_mov_b32_e32 v137, v185
	s_mov_b32 s46, 0
	v_add_u32_e32 v145, 0, v17
	s_movk_i32 s54, 0x1e1
	s_barrier
	s_branch .LBB0_430

; #define PG8_STAGE(bufoff, gbase, voff) do { _Pragma("unroll") for (int _i = 0; _i < 2; ++_i) \
;         __builtin_amdgcn_global_load_lds((const unsigned*)((const char*)(gbase) + (voff)[_i]), (LAS unsigned*)(lds + (bufoff) + ldsw + _i * 8192), 16, 0, 0); } while (0)
; #define PG8_WAIT_V(n) asm volatile("s_waitcnt vmcnt(" #n ")" ::: "memory")
; #define PG8_BAR __builtin_amdgcn_s_barrier()
; template <class Epi>
; __device__ __forceinline__ void gemm_phase(LAS unsigned char* lds, const Gemm g, const StaticOrder& S, const Epi& E) {
;     ...
;     for (int i = 0; i < 2; ++i) { int R, C; stage_rc(tid * 16 + i * 8192, R, C); const int Rb = Epi::PERM ? ((R & ~31) + perm32(R & 31)) : R;
;         voffA[i] = (unsigned)(R * K + C) * 2u; voffB[i] = (unsigned)(Rb * K + C) * 2u; }
;     const size_t kstep = (size_t)(BK * 2);
;     const size_t hstep = (size_t)HALF * K * 2;
;     const size_t tstep = 2 * hstep;
;     const unsigned ldsw = (unsigned)wid * 1024u;
;     const int aoff = lds_byte(wr * 64 + fr, fq * 8), boff = lds_byte(wc * 32 + fr, fq * 8);
;     ...
;     Unit cur, nxt; int ui = 0;
;     if (!S.next(0, cur)) return;
;     f32x4 acc[2][2][4][2];
; #pragma unroll
;     for (int a = 0; a < 2; ++a)
; #pragma unroll
;         for (int b = 0; b < 2; ++b)
; #pragma unroll
;             for (int m = 0; m < 4; ++m)
; #pragma unroll
;                 for (int n = 0; n < 2; ++n) acc[a][b][m][n] = (f32x4){0.f, 0.f, 0.f, 0.f};
;     bf16x8 At[4][2], B0[2][2], B1[2][2];
;     const char* cA = (const char*)g.A + (size_t)cur.pm * tstep; const char* cB = (const char*)g.Bt + (size_t)cur.pn * tstep;
;     PG8_STAGE(PG8_SB(0, 0), cB, voffB); PG8_STAGE(PG8_SA(0, 0), cA, voffA); PG8_STAGE(PG8_SB(0, 1), cB + hstep, voffB); PG8_STAGE(PG8_SA(0, 1), cA + hstep, voffA);
;     if (wr == 1) PG8_BAR;
;     PG8_WAIT_V(4); PG8_BAR;
;     PG8_STAGE(PG8_SB(1, 0), cB + kstep, voffB); PG8_STAGE(PG8_SA(1, 0), cA + kstep, voffA); PG8_STAGE(PG8_SB(1, 1), cB + hstep + kstep, voffB);
;     PG8_WAIT_V(6); PG8_BAR;
.LBB0_582:
	s_add_i32 m0, s44, 0x18000
	v_lshl_add_u64 v[0:1], v[0:1], 0, s[58:59]
	s_waitcnt vmcnt(4)
	s_barrier
	global_load_lds_dwordx4 v[0:1], off
	v_lshl_add_u64 v[0:1], v[2:3], 0, s[58:59]
	s_add_i32 m0, s44, 0x1a000
	s_add_i32 s50, s44, 0x8000
	global_load_lds_dwordx4 v[0:1], off
	v_lshl_add_u64 v[0:1], v[4:5], 0, s[58:59]
	s_mov_b32 m0, s50
	s_add_i32 s51, s44, 0xa000
	global_load_lds_dwordx4 v[0:1], off
	v_lshl_add_u64 v[0:1], v[6:7], 0, s[58:59]
	s_mov_b32 m0, s51
	s_lshr_b32 s54, s6, 6
	global_load_lds_dwordx4 v[0:1], off
	s_add_i32 m0, s44, 0x1c000
	v_lshl_add_u64 v[0:1], v[8:9], 0, s[58:59]
	global_load_lds_dwordx4 v[0:1], off
	v_lshl_add_u64 v[0:1], v[10:11], 0, s[58:59]
	s_add_i32 m0, s44, 0x1e000
	s_lshl_b32 s6, s8, 13
	global_load_lds_dwordx4 v[0:1], off
	v_lshrrev_b32_e32 v1, 1, v12
	v_and_b32_e32 v1, 24, v1
	v_and_b32_e32 v0, 15, v12
	v_lshlrev_b32_e32 v2, 1, v1
	v_lshl_or_b32 v232, s8, 6, v0
	v_lshl_or_b32 v0, v0, 6, v2
	v_lshlrev_b32_e32 v2, 2, v12
	v_and_b32_e32 v2, 32, v2
	v_bitop3_b32 v3, v0, s6, v2 bitop3:0xde
	s_lshl_b32 s6, s7, 5
	s_and_b32 s6, s6, 0x60
	s_lshl_b32 s7, s6, 7
	v_bitop3_b32 v233, v0, s7, v2 bitop3:0xde
	v_add_u32_e32 v233, 0x10000, v233
	v_add_u32_e32 v0, v15, v13
	v_or_b32_e32 v247, s6, v1
	v_add_lshl_u32 v0, v0, v14, 1
	v_mov_b32_e32 v1, v185
	s_waitcnt vmcnt(6)
	s_add_i32 s55, s54, -2
	s_ashr_i32 s56, s38, 31
	v_lshl_add_u64 v[214:215], s[52:53], 0, v[0:1]
	v_add_u32_e32 v0, v18, v16
	s_cmp_lg_u64 s[14:15], 0
	v_add_lshl_u32 v0, v0, v17, 1
	s_cselect_b64 s[30:31], -1, 0
	v_lshl_add_u64 v[216:217], s[52:53], 0, v[0:1]
	s_mov_b32 s57, 0
	v_add_u32_e32 v248, 0, v3
	s_barrier
	s_branch .LBB0_584

; #define PG8_STAGE(bufoff, gbase, voff) do { _Pragma("unroll") for (int _i = 0; _i < 2; ++_i) \
;         __builtin_amdgcn_global_load_lds((const unsigned*)((const char*)(gbase) + (voff)[_i]), (LAS unsigned*)(lds + (bufoff) + ldsw + _i * 8192), 16, 0, 0); } while (0)
; #define PG8_LDA(dst, b, h) do { _Pragma("unroll") for (int m = 0; m < 4; ++m) _Pragma("unroll") for (int k = 0; k < 2; ++k) dst[m][k] = *(const LAS bf16x8*)(lds + PG8_SA(b, h) + aoff + m * 2048 + k * 1024); } while (0)
; #define PG8_LDB(dst, b, h) do { _Pragma("unroll") for (int n = 0; n < 2; ++n) _Pragma("unroll") for (int k = 0; k < 2; ++k) dst[n][k] = *(const LAS bf16x8*)(lds + PG8_SB(b, h) + boff + n * 2048 + k * 1024); } while (0)
; #define PG8_MMA(ai, bj, At, Bt) do { __builtin_amdgcn_s_setprio(1); _Pragma("unroll") for (int m = 0; m < 4; ++m) _Pragma("unroll") for (int n = 0; n < 2; ++n) _Pragma("unroll") for (int k = 0; k < 2; ++k) \
;         acc[ai][bj][m][n] = __builtin_amdgcn_mfma_f32_16x16x32_bf16(Bt[n][k], At[m][k], acc[ai][bj][m][n], 0, 0, 0); __builtin_amdgcn_s_setprio(0); } while (0)
; #define PG8_WAIT_L(n) asm volatile("s_waitcnt lgkmcnt(" #n ")" ::: "memory")
; #define PG8_BAR __builtin_amdgcn_s_barrier()
; #define PG8_SCHED __builtin_amdgcn_sched_barrier(0)
; template <class Epi>
; __device__ __forceinline__ void gemm_phase(LAS unsigned char* lds, const Gemm g, const StaticOrder& S, const Epi& E) {
;     ...
;         for (int t = 0; t < nt; t += 2) {
;             const bool last = (t == nt - 2);
;             const char* a1 = cA + (size_t)(t + 1) * kstep;
;             const char* a2 = last ? nA : cA + (size_t)(t + 2) * kstep; const char* b2 = last ? nB : cB + (size_t)(t + 2) * kstep;
;             const char* a3 = a2 + kstep; const char* b3 = b2 + kstep;
;             PG8_LDB(B0, 0, 0); PG8_SCHED; PG8_LDA(At, 0, 0); PG8_STAGE(PG8_SA(1, 1), a1 + hstep, voffA);
;             PG8_WAIT_L(8); PG8_BAR; PG8_WAIT_L(0); PG8_MMA(0, 0, At, B0); PG8_BAR; PG8_SCHED;
;             PG8_LDB(B1, 0, 1); PG8_STAGE(PG8_SB(0, 0), b2, voffB);
;             PG8_BAR; PG8_WAIT_L(0); PG8_MMA(0, 1, At, B1); PG8_BAR;
;             PG8_LDA(At, 0, 1); PG8_STAGE(PG8_SA(0, 0), a2, voffA);
;             PG8_BAR; PG8_WAIT_L(0); PG8_MMA(1, 0, At, B0); PG8_BAR; PG8_SCHED;
.LBB0_591:
	s_add_i32 s68, s8, 2
	s_add_u32 s36, s0, 0x80
	s_addc_u32 s9, s1, 0
	s_add_i32 s66, 0, 0x10000
	ds_read_b128 v[48:51], v233
	ds_read_b128 v[52:55], v233 offset:1024
	ds_read_b128 v[56:59], v233 offset:2048
	ds_read_b128 v[60:63], v233 offset:3072
	s_cmp_eq_u32 s55, s8
	s_cselect_b32 s8, s34, s36
	s_cselect_b32 s9, s35, s9
	s_cselect_b32 s37, s11, s63
	s_cselect_b32 s36, s10, s43
	v_lshl_add_u64 v[176:177], s[0:1], 0, v[214:215]
	s_add_i32 m0, s44, 0xc000
	ds_read_b128 v[68:71], v248
	ds_read_b128 v[76:79], v248 offset:1024
	ds_read_b128 v[80:83], v248 offset:2048
	ds_read_b128 v[84:87], v248 offset:3072
	ds_read_b128 v[160:163], v248 offset:4096
	ds_read_b128 v[164:167], v248 offset:5120
	ds_read_b128 v[168:171], v248 offset:6144
	ds_read_b128 v[172:175], v248 offset:7168
	global_load_lds_dwordx4 v[176:177], off
	v_lshl_add_u64 v[176:177], s[0:1], 0, v[216:217]
	s_add_i32 m0, s44, 0xe000
	s_nop 0
	global_load_lds_dwordx4 v[176:177], off
	s_waitcnt lgkmcnt(8)
	s_barrier
	s_waitcnt lgkmcnt(0)
	s_waitcnt lgkmcnt(0)
	v_mfma_f32_16x16x32_bf16 v[156:159], v[48:51], v[68:71], v[156:159]
	v_mfma_f32_16x16x32_bf16 v[156:159], v[52:55], v[76:79], v[156:159]
	v_mfma_f32_16x16x32_bf16 v[140:143], v[48:51], v[80:83], v[140:143]
	v_mfma_f32_16x16x32_bf16 v[140:143], v[52:55], v[84:87], v[140:143]
	v_mfma_f32_16x16x32_bf16 v[124:127], v[48:51], v[160:163], v[124:127]
	v_mfma_f32_16x16x32_bf16 v[124:127], v[52:55], v[164:167], v[124:127]
	v_mfma_f32_16x16x32_bf16 v[108:111], v[48:51], v[168:171], v[108:111]
	v_mfma_f32_16x16x32_bf16 v[108:111], v[52:55], v[172:175], v[108:111]
	v_mfma_f32_16x16x32_bf16 v[104:107], v[56:59], v[168:171], v[104:107]
	v_mfma_f32_16x16x32_bf16 v[104:107], v[60:63], v[172:175], v[104:107]
	v_mfma_f32_16x16x32_bf16 v[120:123], v[56:59], v[160:163], v[120:123]
	v_mfma_f32_16x16x32_bf16 v[120:123], v[60:63], v[164:167], v[120:123]
	v_mfma_f32_16x16x32_bf16 v[136:139], v[56:59], v[80:83], v[136:139]
	v_mfma_f32_16x16x32_bf16 v[136:139], v[60:63], v[84:87], v[136:139]
	v_mfma_f32_16x16x32_bf16 v[152:155], v[56:59], v[68:71], v[152:155]
	v_mfma_f32_16x16x32_bf16 v[152:155], v[60:63], v[76:79], v[152:155]
	s_barrier
	s_add_i32 s67, 0, 0x14000
	s_add_i32 s66, s66, s41
	v_lshl_add_u64 v[230:231], s[36:37], 0, v[184:185]
	s_mov_b32 m0, s66
	ds_read_b128 v[176:179], v233 offset:16384
	ds_read_b128 v[180:183], v233 offset:17408
	ds_read_b128 v[218:221], v233 offset:18432
	ds_read_b128 v[222:225], v233 offset:19456
	global_load_lds_dwordx4 v[230:231], off
	v_lshl_add_u64 v[250:251], s[36:37], 0, v[212:213]
	s_add_i32 m0, s66, 0x2000
	s_nop 0
	global_load_lds_dwordx4 v[250:251], off
	s_barrier
	s_waitcnt lgkmcnt(0)
	s_waitcnt lgkmcnt(0)
	v_mfma_f32_16x16x32_bf16 v[148:151], v[176:179], v[68:71], v[148:151]
	v_mfma_f32_16x16x32_bf16 v[68:71], v[218:221], v[68:71], v[144:147]
	v_mfma_f32_16x16x32_bf16 v[148:151], v[180:183], v[76:79], v[148:151]
	v_mfma_f32_16x16x32_bf16 v[68:71], v[222:225], v[76:79], v[68:71]
	v_mfma_f32_16x16x32_bf16 v[76:79], v[176:179], v[80:83], v[132:135]
	v_mfma_f32_16x16x32_bf16 v[80:83], v[218:221], v[80:83], v[128:131]
	v_mfma_f32_16x16x32_bf16 v[112:115], v[218:221], v[160:163], v[112:115]
	v_mfma_f32_16x16x32_bf16 v[100:103], v[176:179], v[168:171], v[100:103]
	v_mfma_f32_16x16x32_bf16 v[96:99], v[218:221], v[168:171], v[96:99]
	v_mfma_f32_16x16x32_bf16 v[76:79], v[180:183], v[84:87], v[76:79]
	v_mfma_f32_16x16x32_bf16 v[80:83], v[222:225], v[84:87], v[80:83]
	v_mfma_f32_16x16x32_bf16 v[84:87], v[176:179], v[160:163], v[116:119]
	v_mfma_f32_16x16x32_bf16 v[112:115], v[222:225], v[164:167], v[112:115]
	v_mfma_f32_16x16x32_bf16 v[100:103], v[180:183], v[172:175], v[100:103]
	v_mfma_f32_16x16x32_bf16 v[96:99], v[222:225], v[172:175], v[96:99]
	v_mfma_f32_16x16x32_bf16 v[84:87], v[180:183], v[164:167], v[84:87]
	s_mov_b32 m0, s44
	v_lshl_add_u64 v[238:239], s[8:9], 0, v[208:209]
	s_barrier
	ds_read_b128 v[116:119], v248 offset:16384
	ds_read_b128 v[128:131], v248 offset:17408
	ds_read_b128 v[132:135], v248 offset:18432
	ds_read_b128 v[144:147], v248 offset:19456
	ds_read_b128 v[160:163], v248 offset:20480
	ds_read_b128 v[164:167], v248 offset:21504
	ds_read_b128 v[168:171], v248 offset:22528
	ds_read_b128 v[172:175], v248 offset:23552
	global_load_lds_dwordx4 v[238:239], off
	v_lshl_add_u64 v[188:189], s[8:9], 0, v[210:211]
	s_mov_b32 m0, s45
	s_nop 0
	global_load_lds_dwordx4 v[188:189], off
	s_barrier
	s_waitcnt lgkmcnt(0)
	s_waitcnt lgkmcnt(0)
	v_mfma_f32_16x16x32_bf16 v[92:95], v[48:51], v[116:119], v[92:95]
	v_mfma_f32_16x16x32_bf16 v[92:95], v[52:55], v[128:131], v[92:95]
	v_mfma_f32_16x16x32_bf16 v[44:47], v[48:51], v[132:135], v[44:47]
	v_mfma_f32_16x16x32_bf16 v[44:47], v[52:55], v[144:147], v[44:47]
	v_mfma_f32_16x16x32_bf16 v[28:31], v[48:51], v[160:163], v[28:31]
	v_mfma_f32_16x16x32_bf16 v[28:31], v[52:55], v[164:167], v[28:31]
	v_mfma_f32_16x16x32_bf16 v[12:15], v[48:51], v[168:171], v[12:15]
	v_mfma_f32_16x16x32_bf16 v[12:15], v[52:55], v[172:175], v[12:15]
	v_mfma_f32_16x16x32_bf16 v[8:11], v[56:59], v[168:171], v[8:11]
	v_mfma_f32_16x16x32_bf16 v[8:11], v[60:63], v[172:175], v[8:11]
	v_mfma_f32_16x16x32_bf16 v[24:27], v[56:59], v[160:163], v[24:27]
	v_mfma_f32_16x16x32_bf16 v[24:27], v[60:63], v[164:167], v[24:27]
	v_mfma_f32_16x16x32_bf16 v[40:43], v[56:59], v[132:135], v[40:43]
	v_mfma_f32_16x16x32_bf16 v[40:43], v[60:63], v[144:147], v[40:43]
	v_mfma_f32_16x16x32_bf16 v[88:91], v[56:59], v[116:119], v[88:91]
	v_mfma_f32_16x16x32_bf16 v[88:91], v[60:63], v[128:131], v[88:91]
	s_barrier
; #define PG8_STAGE(bufoff, gbase, voff) do { _Pragma("unroll") for (int _i = 0; _i < 2; ++_i) \
;         __builtin_amdgcn_global_load_lds((const unsigned*)((const char*)(gbase) + (voff)[_i]), (LAS unsigned*)(lds + (bufoff) + ldsw + _i * 8192), 16, 0, 0); } while (0)
; #define PG8_LDA(dst, b, h) do { _Pragma("unroll") for (int m = 0; m < 4; ++m) _Pragma("unroll") for (int k = 0; k < 2; ++k) dst[m][k] = *(const LAS bf16x8*)(lds + PG8_SA(b, h) + aoff + m * 2048 + k * 1024); } while (0)
; #define PG8_LDB(dst, b, h) do { _Pragma("unroll") for (int n = 0; n < 2; ++n) _Pragma("unroll") for (int k = 0; k < 2; ++k) dst[n][k] = *(const LAS bf16x8*)(lds + PG8_SB(b, h) + boff + n * 2048 + k * 1024); } while (0)
; #define PG8_MMA(ai, bj, At, Bt) do { __builtin_amdgcn_s_setprio(1); _Pragma("unroll") for (int m = 0; m < 4; ++m) _Pragma("unroll") for (int n = 0; n < 2; ++n) _Pragma("unroll") for (int k = 0; k < 2; ++k) \
;         acc[ai][bj][m][n] = __builtin_amdgcn_mfma_f32_16x16x32_bf16(Bt[n][k], At[m][k], acc[ai][bj][m][n], 0, 0, 0); __builtin_amdgcn_s_setprio(0); } while (0)
; #define PG8_WAIT_V(n) asm volatile("s_waitcnt vmcnt(" #n ")" ::: "memory")
; #define PG8_WAIT_L(n) asm volatile("s_waitcnt lgkmcnt(" #n ")" ::: "memory")
; #define PG8_BAR __builtin_amdgcn_s_barrier()
; #define PG8_SCHED __builtin_amdgcn_sched_barrier(0)
; template <class Epi>
; __device__ __forceinline__ void gemm_phase(LAS unsigned char* lds, const Gemm g, const StaticOrder& S, const Epi& E) {
;     ...
;             PG8_STAGE(PG8_SB(0, 1), b2 + hstep, voffB);
;             PG8_WAIT_V(6); PG8_BAR; PG8_MMA(1, 1, At, B1); PG8_BAR;
;             PG8_LDB(B0, 1, 0); PG8_SCHED; PG8_LDA(At, 1, 0); PG8_STAGE(PG8_SA(0, 1), a2 + hstep, voffA);
;             PG8_WAIT_L(8); PG8_BAR; PG8_WAIT_L(0); PG8_MMA(0, 0, At, B0); PG8_BAR; PG8_SCHED;
;             PG8_LDB(B1, 1, 1); PG8_STAGE(PG8_SB(1, 0), b3, voffB);
;             PG8_BAR; PG8_WAIT_L(0); PG8_MMA(0, 1, At, B1); PG8_BAR;
	s_add_u32 s36, s36, s52
	s_addc_u32 s37, s37, 0
	s_add_i32 s66, s67, s41
	v_lshl_add_u64 v[190:191], s[36:37], 0, v[184:185]
	s_mov_b32 m0, s66
	v_lshl_add_u64 v[192:193], s[36:37], 0, v[212:213]
	global_load_lds_dwordx4 v[190:191], off
	s_add_i32 m0, s66, 0x2000
	s_nop 0
	global_load_lds_dwordx4 v[192:193], off
	s_waitcnt vmcnt(6)
	s_barrier
	v_mfma_f32_16x16x32_bf16 v[36:39], v[176:179], v[132:135], v[36:39]
	v_mfma_f32_16x16x32_bf16 v[36:39], v[180:183], v[144:147], v[36:39]
	v_mfma_f32_16x16x32_bf16 v[20:23], v[176:179], v[160:163], v[20:23]
	v_mfma_f32_16x16x32_bf16 v[20:23], v[180:183], v[164:167], v[20:23]
	v_mfma_f32_16x16x32_bf16 v[4:7], v[176:179], v[168:171], v[4:7]
	v_mfma_f32_16x16x32_bf16 v[4:7], v[180:183], v[172:175], v[4:7]
	v_mfma_f32_16x16x32_bf16 v[48:51], v[176:179], v[116:119], v[72:75]
	v_mfma_f32_16x16x32_bf16 v[48:51], v[180:183], v[128:131], v[48:51]
	v_mfma_f32_16x16x32_bf16 v[52:55], v[218:221], v[116:119], v[64:67]
	v_mfma_f32_16x16x32_bf16 v[52:55], v[222:225], v[128:131], v[52:55]
	v_mfma_f32_16x16x32_bf16 v[0:3], v[218:221], v[168:171], v[0:3]
	v_mfma_f32_16x16x32_bf16 v[0:3], v[222:225], v[172:175], v[0:3]
	v_mfma_f32_16x16x32_bf16 v[16:19], v[218:221], v[160:163], v[16:19]
	v_mfma_f32_16x16x32_bf16 v[16:19], v[222:225], v[164:167], v[16:19]
	v_mfma_f32_16x16x32_bf16 v[32:35], v[218:221], v[132:135], v[32:35]
	v_mfma_f32_16x16x32_bf16 v[32:35], v[222:225], v[144:147], v[32:35]
	s_add_i32 s36, 0, 0x18000
	s_barrier
	ds_read_b128 v[56:59], v233 offset:32768
	ds_read_b128 v[60:63], v233 offset:33792
	ds_read_b128 v[64:67], v233 offset:34816
	ds_read_b128 v[72:75], v233 offset:35840
	s_add_u32 s8, s8, s52
	s_addc_u32 s9, s9, 0
	s_mov_b32 m0, s46
	v_lshl_add_u64 v[132:133], s[8:9], 0, v[208:209]
	ds_read_b128 v[116:119], v248 offset:32768
	ds_read_b128 v[128:131], v248 offset:33792
	ds_read_b128 v[160:163], v248 offset:34816
	ds_read_b128 v[164:167], v248 offset:35840
	ds_read_b128 v[168:171], v248 offset:36864
	ds_read_b128 v[172:175], v248 offset:37888
	ds_read_b128 v[176:179], v248 offset:38912
	ds_read_b128 v[180:183], v248 offset:39936
	global_load_lds_dwordx4 v[132:133], off
	v_lshl_add_u64 v[132:133], s[8:9], 0, v[210:211]
	s_mov_b32 m0, s47
	s_nop 0
	global_load_lds_dwordx4 v[132:133], off
	s_waitcnt lgkmcnt(8)
	s_barrier
	s_waitcnt lgkmcnt(0)
	s_waitcnt lgkmcnt(0)
	v_mfma_f32_16x16x32_bf16 v[132:135], v[56:59], v[116:119], v[156:159]
	v_mfma_f32_16x16x32_bf16 v[156:159], v[60:63], v[128:131], v[132:135]
	v_mfma_f32_16x16x32_bf16 v[132:135], v[64:67], v[116:119], v[152:155]
	v_mfma_f32_16x16x32_bf16 v[152:155], v[72:75], v[128:131], v[132:135]
	v_mfma_f32_16x16x32_bf16 v[132:135], v[56:59], v[160:163], v[140:143]
	v_mfma_f32_16x16x32_bf16 v[140:143], v[60:63], v[164:167], v[132:135]
	v_mfma_f32_16x16x32_bf16 v[132:135], v[64:67], v[160:163], v[136:139]
	v_mfma_f32_16x16x32_bf16 v[124:127], v[56:59], v[168:171], v[124:127]
	v_mfma_f32_16x16x32_bf16 v[120:123], v[64:67], v[168:171], v[120:123]
	v_mfma_f32_16x16x32_bf16 v[108:111], v[56:59], v[176:179], v[108:111]
	v_mfma_f32_16x16x32_bf16 v[104:107], v[64:67], v[176:179], v[104:107]
	v_mfma_f32_16x16x32_bf16 v[136:139], v[72:75], v[164:167], v[132:135]
	v_mfma_f32_16x16x32_bf16 v[124:127], v[60:63], v[172:175], v[124:127]
	v_mfma_f32_16x16x32_bf16 v[120:123], v[72:75], v[172:175], v[120:123]
	v_mfma_f32_16x16x32_bf16 v[108:111], v[60:63], v[180:183], v[108:111]
	v_mfma_f32_16x16x32_bf16 v[104:107], v[72:75], v[180:183], v[104:107]
	s_barrier
	s_add_i32 s8, 0, 0x1c000
	s_add_i32 s9, s36, s41
	ds_read_b128 v[218:221], v233 offset:49152
	ds_read_b128 v[222:225], v233 offset:50176
	ds_read_b128 v[226:229], v233 offset:51200
	ds_read_b128 v[204:207], v233 offset:52224
	v_lshl_add_u64 v[132:133], v[230:231], 0, s[58:59]
	s_mov_b32 m0, s9
	s_nop 0
	global_load_lds_dwordx4 v[132:133], off
	v_lshl_add_u64 v[132:133], v[250:251], 0, s[58:59]
	s_add_i32 m0, s9, 0x2000
	s_nop 0
	global_load_lds_dwordx4 v[132:133], off
	s_barrier
; #define PG8_STAGE(bufoff, gbase, voff) do { _Pragma("unroll") for (int _i = 0; _i < 2; ++_i) \
;         __builtin_amdgcn_global_load_lds((const unsigned*)((const char*)(gbase) + (voff)[_i]), (LAS unsigned*)(lds + (bufoff) + ldsw + _i * 8192), 16, 0, 0); } while (0)
; #define PG8_LDA(dst, b, h) do { _Pragma("unroll") for (int m = 0; m < 4; ++m) _Pragma("unroll") for (int k = 0; k < 2; ++k) dst[m][k] = *(const LAS bf16x8*)(lds + PG8_SA(b, h) + aoff + m * 2048 + k * 1024); } while (0)
; #define PG8_MMA(ai, bj, At, Bt) do { __builtin_amdgcn_s_setprio(1); _Pragma("unroll") for (int m = 0; m < 4; ++m) _Pragma("unroll") for (int n = 0; n < 2; ++n) _Pragma("unroll") for (int k = 0; k < 2; ++k) \
;         acc[ai][bj][m][n] = __builtin_amdgcn_mfma_f32_16x16x32_bf16(Bt[n][k], At[m][k], acc[ai][bj][m][n], 0, 0, 0); __builtin_amdgcn_s_setprio(0); } while (0)
; #define PG8_WAIT_V(n) asm volatile("s_waitcnt vmcnt(" #n ")" ::: "memory")
; #define PG8_BAR __builtin_amdgcn_s_barrier()
; template <class Epi>
; __device__ __forceinline__ void gemm_phase(LAS unsigned char* lds, const Gemm g, const StaticOrder& S, const Epi& E) {
;     ...
;             PG8_BAR; PG8_WAIT_L(0); PG8_MMA(0, 1, At, B1); PG8_BAR;
;             PG8_LDA(At, 1, 1); PG8_STAGE(PG8_SA(1, 0), a3, voffA);
;             PG8_BAR; PG8_WAIT_L(0); PG8_MMA(1, 0, At, B0); PG8_BAR; PG8_SCHED;
;             PG8_STAGE(PG8_SB(1, 1), b3 + hstep, voffB);
;             PG8_WAIT_V(6); PG8_BAR; PG8_MMA(1, 1, At, B1); PG8_BAR;
;         }
;     __device__ __forceinline__ void operator()(const Acc& acc, const Unit& u, int wr, int wc, int fr, int fq) const {
;         const int row0 = u.pm * 256 + wr * 64 + fr, col0 = u.pn * 256 + wc * 32 + 8 * fq;
;         const bf16_t* __restrict__ xr = xres; bf16_t* __restrict__ op = out;
;         f32x4 gv[2][2], bv[2][2];
;         if (stats) {
; #pragma unroll
;             for (int bj = 0; bj < 2; ++bj)
; #pragma unroll
;                 for (int n = 0; n < 2; ++n) { gv[bj][n] = *(const f32x4*)(lg + col0 + bj * 128 + n * 4); bv[bj][n] = *(const f32x4*)(lb + col0 + bj * 128 + n * 4); } }
;         u32x4 xv[2][2]; float mu[2], rs[2];
; #pragma unroll
;         for (int bj = 0; bj < 2; ++bj) xv[0][bj] = *(const u32x4*)(xr + (size_t)row0 * DM + col0 + bj * 128);
;         mu[0] = 0.f; rs[0] = 1.f;
;         if (stats) { mu[0] = stats[(size_t)row0 * 2]; rs[0] = stats[(size_t)row0 * 2 + 1]; }
	s_waitcnt lgkmcnt(0)
	s_waitcnt lgkmcnt(0)
	v_mfma_f32_16x16x32_bf16 v[68:71], v[226:229], v[116:119], v[68:71]
	v_mfma_f32_16x16x32_bf16 v[132:135], v[218:221], v[116:119], v[148:151]
	v_mfma_f32_16x16x32_bf16 v[144:147], v[204:207], v[128:131], v[68:71]
	v_mfma_f32_16x16x32_bf16 v[68:71], v[218:221], v[160:163], v[76:79]
	v_mfma_f32_16x16x32_bf16 v[148:151], v[222:225], v[128:131], v[132:135]
	v_mfma_f32_16x16x32_bf16 v[132:135], v[222:225], v[164:167], v[68:71]
	v_mfma_f32_16x16x32_bf16 v[68:71], v[226:229], v[160:163], v[80:83]
	v_mfma_f32_16x16x32_bf16 v[128:131], v[204:207], v[164:167], v[68:71]
	v_mfma_f32_16x16x32_bf16 v[68:71], v[218:221], v[168:171], v[84:87]
	v_mfma_f32_16x16x32_bf16 v[116:119], v[222:225], v[172:175], v[68:71]
	v_mfma_f32_16x16x32_bf16 v[68:71], v[226:229], v[168:171], v[112:115]
	v_mfma_f32_16x16x32_bf16 v[112:115], v[204:207], v[172:175], v[68:71]
	v_mfma_f32_16x16x32_bf16 v[68:71], v[218:221], v[176:179], v[100:103]
	v_mfma_f32_16x16x32_bf16 v[100:103], v[222:225], v[180:183], v[68:71]
	v_mfma_f32_16x16x32_bf16 v[68:71], v[226:229], v[176:179], v[96:99]
	v_mfma_f32_16x16x32_bf16 v[96:99], v[204:207], v[180:183], v[68:71]
	s_mov_b32 m0, s50
	v_lshl_add_u64 v[176:177], v[238:239], 0, s[58:59]
	s_barrier
	s_nop 2
	ds_read_b128 v[68:71], v248 offset:49152
	ds_read_b128 v[76:79], v248 offset:50176
	ds_read_b128 v[80:83], v248 offset:51200
	ds_read_b128 v[84:87], v248 offset:52224
	ds_read_b128 v[160:163], v248 offset:53248
	ds_read_b128 v[164:167], v248 offset:54272
	ds_read_b128 v[168:171], v248 offset:55296
	ds_read_b128 v[172:175], v248 offset:56320
	global_load_lds_dwordx4 v[176:177], off
	v_lshl_add_u64 v[176:177], v[188:189], 0, s[58:59]
	s_mov_b32 m0, s51
	s_nop 0
	global_load_lds_dwordx4 v[176:177], off
	s_barrier
	s_waitcnt lgkmcnt(0)
	s_waitcnt lgkmcnt(0)
	v_mfma_f32_16x16x32_bf16 v[92:95], v[56:59], v[68:71], v[92:95]
	v_mfma_f32_16x16x32_bf16 v[92:95], v[60:63], v[76:79], v[92:95]
	v_mfma_f32_16x16x32_bf16 v[44:47], v[56:59], v[80:83], v[44:47]
	v_mfma_f32_16x16x32_bf16 v[44:47], v[60:63], v[84:87], v[44:47]
	v_mfma_f32_16x16x32_bf16 v[28:31], v[56:59], v[160:163], v[28:31]
	v_mfma_f32_16x16x32_bf16 v[28:31], v[60:63], v[164:167], v[28:31]
	v_mfma_f32_16x16x32_bf16 v[12:15], v[56:59], v[168:171], v[12:15]
	v_mfma_f32_16x16x32_bf16 v[12:15], v[60:63], v[172:175], v[12:15]
	v_mfma_f32_16x16x32_bf16 v[8:11], v[64:67], v[168:171], v[8:11]
	v_mfma_f32_16x16x32_bf16 v[8:11], v[72:75], v[172:175], v[8:11]
	v_mfma_f32_16x16x32_bf16 v[24:27], v[64:67], v[160:163], v[24:27]
	v_mfma_f32_16x16x32_bf16 v[24:27], v[72:75], v[164:167], v[24:27]
	v_mfma_f32_16x16x32_bf16 v[40:43], v[64:67], v[80:83], v[40:43]
	v_mfma_f32_16x16x32_bf16 v[40:43], v[72:75], v[84:87], v[40:43]
	v_mfma_f32_16x16x32_bf16 v[88:91], v[64:67], v[68:71], v[88:91]
	v_mfma_f32_16x16x32_bf16 v[88:91], v[72:75], v[76:79], v[88:91]
	s_barrier
	s_add_i32 s8, s8, s41
	v_lshl_add_u64 v[56:57], v[190:191], 0, s[58:59]
	s_mov_b32 m0, s8
	s_nop 0
	global_load_lds_dwordx4 v[56:57], off
	v_lshl_add_u64 v[56:57], v[192:193], 0, s[58:59]
	s_add_i32 m0, s8, 0x2000
	s_nop 0
	global_load_lds_dwordx4 v[56:57], off
	s_waitcnt vmcnt(6)
	s_barrier
	v_mfma_f32_16x16x32_bf16 v[48:51], v[218:221], v[68:71], v[48:51]
	v_mfma_f32_16x16x32_bf16 v[72:75], v[222:225], v[76:79], v[48:51]
	v_mfma_f32_16x16x32_bf16 v[48:51], v[226:229], v[68:71], v[52:55]
	v_mfma_f32_16x16x32_bf16 v[36:39], v[218:221], v[80:83], v[36:39]
	v_mfma_f32_16x16x32_bf16 v[32:35], v[226:229], v[80:83], v[32:35]
	v_mfma_f32_16x16x32_bf16 v[20:23], v[218:221], v[160:163], v[20:23]
	v_mfma_f32_16x16x32_bf16 v[16:19], v[226:229], v[160:163], v[16:19]
	v_mfma_f32_16x16x32_bf16 v[4:7], v[218:221], v[168:171], v[4:7]
	v_mfma_f32_16x16x32_bf16 v[0:3], v[226:229], v[168:171], v[0:3]
	v_mfma_f32_16x16x32_bf16 v[64:67], v[204:207], v[76:79], v[48:51]
	v_mfma_f32_16x16x32_bf16 v[36:39], v[222:225], v[84:87], v[36:39]
	v_mfma_f32_16x16x32_bf16 v[32:35], v[204:207], v[84:87], v[32:35]
	v_mfma_f32_16x16x32_bf16 v[20:23], v[222:225], v[164:167], v[20:23]
	v_mfma_f32_16x16x32_bf16 v[16:19], v[204:207], v[164:167], v[16:19]
	v_mfma_f32_16x16x32_bf16 v[4:7], v[222:225], v[172:175], v[4:7]
	v_mfma_f32_16x16x32_bf16 v[0:3], v[204:207], v[172:175], v[0:3]
	s_add_u32 s0, s0, 0x100
	s_addc_u32 s1, s1, 0
	s_add_u32 s43, s43, 0x100
	s_addc_u32 s63, s63, 0
	s_cmp_ge_u32 s68, s54
	s_mov_b32 s8, s68
	s_barrier
	s_cbranch_scc0 .LBB0_591
	v_lshl_or_b32 v224, s42, 8, v247
	v_cndmask_b32_e64 v48, 0, 1, s[30:31]
	v_cmp_ne_u32_e64 s[8:9], 1, v48
	s_andn2_b64 vcc, exec, s[30:31]
	v_ashrrev_i32_e32 v225, 31, v224
	s_cbranch_vccnz .LBB0_594
	v_lshlrev_b64 v[48:49], 2, v[224:225]
	v_lshl_add_u64 v[52:53], s[20:21], 0, v[48:49]
	v_lshl_add_u64 v[60:61], s[22:23], 0, v[48:49]
	global_load_dwordx4 v[68:71], v[52:53], off offset:16
	global_load_dwordx4 v[80:83], v[52:53], off
	global_load_dwordx4 v[76:79], v[60:61], off offset:16
	global_load_dwordx4 v[84:87], v[60:61], off
	global_load_dwordx4 v[48:51], v[52:53], off offset:528
	global_load_dwordx4 v[56:59], v[52:53], off offset:512
	s_nop 0
	global_load_dwordx4 v[52:55], v[60:61], off offset:528
	s_nop 0
	global_load_dwordx4 v[60:63], v[60:61], off offset:512

; #define PG8_STAGE(bufoff, gbase, voff) do { _Pragma("unroll") for (int _i = 0; _i < 2; ++_i) \
;         __builtin_amdgcn_global_load_lds((const unsigned*)((const char*)(gbase) + (voff)[_i]), (LAS unsigned*)(lds + (bufoff) + ldsw + _i * 8192), 16, 0, 0); } while (0)
; #define PG8_WAIT_V(n) asm volatile("s_waitcnt vmcnt(" #n ")" ::: "memory")
; #define PG8_BAR __builtin_amdgcn_s_barrier()
; template <class Epi>
; __device__ __forceinline__ void gemm_phase(LAS unsigned char* lds, const Gemm g, const StaticOrder& S, const Epi& E) {
;     ...
;     for (int i = 0; i < 2; ++i) { int R, C; stage_rc(tid * 16 + i * 8192, R, C); const int Rb = Epi::PERM ? ((R & ~31) + perm32(R & 31)) : R;
;         voffA[i] = (unsigned)(R * K + C) * 2u; voffB[i] = (unsigned)(Rb * K + C) * 2u; }
;     const size_t kstep = (size_t)(BK * 2);
;     const size_t hstep = (size_t)HALF * K * 2;
;     const size_t tstep = 2 * hstep;
;     const unsigned ldsw = (unsigned)wid * 1024u;
;     const int aoff = lds_byte(wr * 64 + fr, fq * 8), boff = lds_byte(wc * 32 + fr, fq * 8);
;     ...
;     Unit cur, nxt; int ui = 0;
;     if (!S.next(0, cur)) return;
;     f32x4 acc[2][2][4][2];
; #pragma unroll
;     for (int a = 0; a < 2; ++a)
; #pragma unroll
;         for (int b = 0; b < 2; ++b)
; #pragma unroll
;             for (int m = 0; m < 4; ++m)
; #pragma unroll
;                 for (int n = 0; n < 2; ++n) acc[a][b][m][n] = (f32x4){0.f, 0.f, 0.f, 0.f};
;     bf16x8 At[4][2], B0[2][2], B1[2][2];
;     const char* cA = (const char*)g.A + (size_t)cur.pm * tstep; const char* cB = (const char*)g.Bt + (size_t)cur.pn * tstep;
;     PG8_STAGE(PG8_SB(0, 0), cB, voffB); PG8_STAGE(PG8_SA(0, 0), cA, voffA); PG8_STAGE(PG8_SB(0, 1), cB + hstep, voffB); PG8_STAGE(PG8_SA(0, 1), cA + hstep, voffA);
;     if (wr == 1) PG8_BAR;
;     PG8_WAIT_V(4); PG8_BAR;
;     PG8_STAGE(PG8_SB(1, 0), cB + kstep, voffB); PG8_STAGE(PG8_SA(1, 0), cA + kstep, voffA); PG8_STAGE(PG8_SB(1, 1), cB + hstep + kstep, voffB);
;     PG8_WAIT_V(6); PG8_BAR;
.LBB0_717:
	v_lshl_add_u64 v[8:9], s[18:19], 0, v[184:185]
	v_mov_b32_e32 v129, v185
	s_lshl_b32 s3, s3, 5
	v_lshl_add_u64 v[10:11], s[18:19], 0, v[128:129]
	v_mov_b32_e32 v133, v185
	s_and_b32 s9, s3, 0x60
	s_add_i32 m0, s15, 0x18000
	v_lshl_add_u64 v[8:9], v[8:9], 0, s[58:59]
	v_lshl_add_u64 v[12:13], s[16:17], 0, v[132:133]
	v_mov_b32_e32 v131, v185
	s_lshl_b32 s8, s1, 13
	s_lshl_b32 s10, s9, 7
	s_waitcnt vmcnt(4)
	s_barrier
	global_load_lds_dwordx4 v[8:9], off
	v_lshl_add_u64 v[8:9], v[10:11], 0, s[58:59]
	s_add_i32 m0, s15, 0x1a000
	s_add_i32 s29, s15, 0x8000
	s_add_i32 s30, s15, 0xa000
	v_lshl_add_u64 v[14:15], s[16:17], 0, v[130:131]
	global_load_lds_dwordx4 v[8:9], off
	v_lshl_add_u64 v[8:9], v[12:13], 0, s[58:59]
	s_mov_b32 m0, s29
	s_add_u32 s6, s18, 0x80080
	global_load_lds_dwordx4 v[8:9], off
	v_lshl_add_u64 v[8:9], v[14:15], 0, s[58:59]
	s_mov_b32 m0, s30
	s_addc_u32 s7, s19, 0
	global_load_lds_dwordx4 v[8:9], off
	s_add_i32 m0, s15, 0x1c000
	v_lshl_add_u64 v[8:9], s[6:7], 0, v[184:185]
	global_load_lds_dwordx4 v[8:9], off
	v_lshl_add_u64 v[8:9], s[6:7], 0, v[128:129]
	s_add_i32 m0, s15, 0x1e000
	v_and_b32_e32 v7, 15, v0
	global_load_lds_dwordx4 v[8:9], off
	v_lshrrev_b32_e32 v8, 1, v0
	v_and_b32_e32 v8, 24, v8
	v_lshlrev_b32_e32 v9, 1, v8
	v_lshlrev_b32_e32 v0, 2, v0
	v_lshl_or_b32 v138, s1, 6, v7
	v_lshl_or_b32 v7, v7, 6, v9
	v_and_b32_e32 v0, 32, v0
	v_bitop3_b32 v9, v7, s8, v0 bitop3:0xde
	v_bitop3_b32 v139, v7, s10, v0 bitop3:0xde
	v_add_u32_e32 v139, 0x10000, v139
	v_lshlrev_b32_e32 v0, 15, v5
	v_and_b32_e32 v0, 0xffff0000, v0
	v_lshl_add_u32 v0, v4, 12, v0
	v_and_b32_e32 v4, 1, v5
	v_lshl_or_b32 v0, v4, 6, v0
	v_lshl_add_u32 v134, v6, 1, v0
	v_lshlrev_b32_e32 v0, 15, v1
	v_and_b32_e32 v0, 0xffff0000, v0
	s_waitcnt vmcnt(6)
	v_lshl_add_u32 v0, v2, 12, v0
	v_and_b32_e32 v1, 1, v1
	v_lshl_or_b32 v0, v1, 6, v0
	s_sext_i32_i16 s3, s0
	v_or_b32_e32 v140, s9, v8
	v_mov_b32_e32 v135, v185
	v_lshl_add_u32 v136, v3, 1, v0
	v_mov_b32_e32 v137, v185
	s_mov_b32 s31, 0
	v_add_u32_e32 v141, 0, v9
	s_barrier

; #define PG8_STAGE(bufoff, gbase, voff) do { _Pragma("unroll") for (int _i = 0; _i < 2; ++_i) \
;         __builtin_amdgcn_global_load_lds((const unsigned*)((const char*)(gbase) + (voff)[_i]), (LAS unsigned*)(lds + (bufoff) + ldsw + _i * 8192), 16, 0, 0); } while (0)
; #define PG8_LDA(dst, b, h) do { _Pragma("unroll") for (int m = 0; m < 4; ++m) _Pragma("unroll") for (int k = 0; k < 2; ++k) dst[m][k] = *(const LAS bf16x8*)(lds + PG8_SA(b, h) + aoff + m * 2048 + k * 1024); } while (0)
; #define PG8_LDB(dst, b, h) do { _Pragma("unroll") for (int n = 0; n < 2; ++n) _Pragma("unroll") for (int k = 0; k < 2; ++k) dst[n][k] = *(const LAS bf16x8*)(lds + PG8_SB(b, h) + boff + n * 2048 + k * 1024); } while (0)
; #define PG8_MMA(ai, bj, At, Bt) do { __builtin_amdgcn_s_setprio(1); _Pragma("unroll") for (int m = 0; m < 4; ++m) _Pragma("unroll") for (int n = 0; n < 2; ++n) _Pragma("unroll") for (int k = 0; k < 2; ++k) \
;         acc[ai][bj][m][n] = __builtin_amdgcn_mfma_f32_16x16x32_bf16(Bt[n][k], At[m][k], acc[ai][bj][m][n], 0, 0, 0); __builtin_amdgcn_s_setprio(0); } while (0)
; #define PG8_WAIT_V(n) asm volatile("s_waitcnt vmcnt(" #n ")" ::: "memory")
; #define PG8_WAIT_L(n) asm volatile("s_waitcnt lgkmcnt(" #n ")" ::: "memory")
; template <class Epi>
; __device__ __forceinline__ void gemm_phase(LAS unsigned char* lds, const Gemm g, const StaticOrder& S, const Epi& E) {
;     ...
;         for (int t = 0; t < nt; t += 2) {
;             const bool last = (t == nt - 2);
;             const char* a1 = cA + (size_t)(t + 1) * kstep;
;             const char* a2 = last ? nA : cA + (size_t)(t + 2) * kstep; const char* b2 = last ? nB : cB + (size_t)(t + 2) * kstep;
;             const char* a3 = a2 + kstep; const char* b3 = b2 + kstep;
;             PG8_LDB(B0, 0, 0); PG8_SCHED; PG8_LDA(At, 0, 0); PG8_STAGE(PG8_SA(1, 1), a1 + hstep, voffA);
;             PG8_WAIT_L(8); PG8_BAR; PG8_WAIT_L(0); PG8_MMA(0, 0, At, B0); PG8_BAR; PG8_SCHED;
;             PG8_LDB(B1, 0, 1); PG8_STAGE(PG8_SB(0, 0), b2, voffB);
;             PG8_BAR; PG8_WAIT_L(0); PG8_MMA(0, 1, At, B1); PG8_BAR;
;             PG8_LDA(At, 0, 1); PG8_STAGE(PG8_SA(0, 0), a2, voffA);
;             PG8_BAR; PG8_WAIT_L(0); PG8_MMA(1, 0, At, B0); PG8_BAR; PG8_SCHED;
;             PG8_STAGE(PG8_SB(0, 1), b2 + hstep, voffB);
;             PG8_WAIT_V(6); PG8_BAR; PG8_MMA(1, 1, At, B1); PG8_BAR;
.LBB0_721:
	s_add_u32 s18, s16, 0xfff80080
	s_addc_u32 s19, s17, -1
	s_add_i32 s39, 0, 0x10000
	ds_read_b128 v[142:145], v139
	ds_read_b128 v[146:149], v139 offset:1024
	ds_read_b128 v[150:153], v139 offset:2048
	ds_read_b128 v[154:157], v139 offset:3072
	s_cmp_eq_u32 s38, 28
	s_cselect_b32 s21, s9, s19
	s_cselect_b32 s20, s34, s18
	s_cselect_b32 s19, s1, s37
	s_cselect_b32 s18, s35, s36
	s_add_i32 m0, s15, 0xc000
	ds_read_b128 v[158:161], v141
	ds_read_b128 v[162:165], v141 offset:1024
	ds_read_b128 v[166:169], v141 offset:2048
	ds_read_b128 v[170:173], v141 offset:3072
	ds_read_b128 v[174:177], v141 offset:4096
	ds_read_b128 v[178:181], v141 offset:5120
	ds_read_b128 v[208:211], v141 offset:6144
	ds_read_b128 v[212:215], v141 offset:7168
	global_load_lds_dwordx4 v134, s[16:17]
	s_add_i32 m0, s15, 0xe000
	s_nop 0
	global_load_lds_dwordx4 v136, s[16:17]
	s_waitcnt lgkmcnt(8)
	s_barrier
	s_waitcnt lgkmcnt(0)
	s_waitcnt lgkmcnt(0)
	v_mfma_f32_16x16x32_bf16 v[124:127], v[142:145], v[158:161], v[124:127]
	v_mfma_f32_16x16x32_bf16 v[124:127], v[146:149], v[162:165], v[124:127]
	v_mfma_f32_16x16x32_bf16 v[108:111], v[142:145], v[166:169], v[108:111]
	v_mfma_f32_16x16x32_bf16 v[108:111], v[146:149], v[170:173], v[108:111]
	v_mfma_f32_16x16x32_bf16 v[92:95], v[142:145], v[174:177], v[92:95]
	v_mfma_f32_16x16x32_bf16 v[92:95], v[146:149], v[178:181], v[92:95]
	v_mfma_f32_16x16x32_bf16 v[76:79], v[142:145], v[208:211], v[76:79]
	v_mfma_f32_16x16x32_bf16 v[76:79], v[146:149], v[212:215], v[76:79]
	v_mfma_f32_16x16x32_bf16 v[68:71], v[150:153], v[208:211], v[68:71]
	v_mfma_f32_16x16x32_bf16 v[68:71], v[154:157], v[212:215], v[68:71]
	v_mfma_f32_16x16x32_bf16 v[84:87], v[150:153], v[174:177], v[84:87]
	v_mfma_f32_16x16x32_bf16 v[84:87], v[154:157], v[178:181], v[84:87]
	v_mfma_f32_16x16x32_bf16 v[100:103], v[150:153], v[166:169], v[100:103]
	v_mfma_f32_16x16x32_bf16 v[100:103], v[154:157], v[170:173], v[100:103]
	v_mfma_f32_16x16x32_bf16 v[116:119], v[150:153], v[158:161], v[116:119]
	v_mfma_f32_16x16x32_bf16 v[116:119], v[154:157], v[162:165], v[116:119]
	s_barrier
	s_add_i32 s42, 0, 0x14000
	s_add_i32 s39, s39, s24
	ds_read_b128 v[216:219], v139 offset:16384
	ds_read_b128 v[220:223], v139 offset:17408
	ds_read_b128 v[224:227], v139 offset:18432
	ds_read_b128 v[228:231], v139 offset:19456
	s_mov_b32 m0, s39
	s_add_u32 s98, s18, s58
	s_addc_u32 s99, s19, s59
	global_load_lds_dwordx4 v184, s[18:19]
	s_add_i32 m0, s39, 0x2000
	s_nop 0
	global_load_lds_dwordx4 v128, s[18:19]
	s_barrier
	s_waitcnt lgkmcnt(0)
	s_waitcnt lgkmcnt(0)
	v_mfma_f32_16x16x32_bf16 v[120:123], v[216:219], v[158:161], v[120:123]
	v_mfma_f32_16x16x32_bf16 v[120:123], v[220:223], v[162:165], v[120:123]
	v_mfma_f32_16x16x32_bf16 v[104:107], v[216:219], v[166:169], v[104:107]
	v_mfma_f32_16x16x32_bf16 v[104:107], v[220:223], v[170:173], v[104:107]
	v_mfma_f32_16x16x32_bf16 v[88:91], v[216:219], v[174:177], v[88:91]
	v_mfma_f32_16x16x32_bf16 v[88:91], v[220:223], v[178:181], v[88:91]
	v_mfma_f32_16x16x32_bf16 v[72:75], v[216:219], v[208:211], v[72:75]
	v_mfma_f32_16x16x32_bf16 v[72:75], v[220:223], v[212:215], v[72:75]
	v_mfma_f32_16x16x32_bf16 v[64:67], v[224:227], v[208:211], v[64:67]
	v_mfma_f32_16x16x32_bf16 v[64:67], v[228:231], v[212:215], v[64:67]
	v_mfma_f32_16x16x32_bf16 v[80:83], v[224:227], v[174:177], v[80:83]
	v_mfma_f32_16x16x32_bf16 v[80:83], v[228:231], v[178:181], v[80:83]
	v_mfma_f32_16x16x32_bf16 v[96:99], v[224:227], v[166:169], v[96:99]
	v_mfma_f32_16x16x32_bf16 v[96:99], v[228:231], v[170:173], v[96:99]
	v_mfma_f32_16x16x32_bf16 v[112:115], v[224:227], v[158:161], v[112:115]
	v_mfma_f32_16x16x32_bf16 v[112:115], v[228:231], v[162:165], v[112:115]
	s_mov_b32 m0, s15
	s_barrier
	ds_read_b128 v[158:161], v141 offset:16384
	ds_read_b128 v[162:165], v141 offset:17408
	ds_read_b128 v[166:169], v141 offset:18432
	ds_read_b128 v[170:173], v141 offset:19456
	ds_read_b128 v[174:177], v141 offset:20480
	ds_read_b128 v[178:181], v141 offset:21504
	ds_read_b128 v[208:211], v141 offset:22528
	ds_read_b128 v[212:215], v141 offset:23552
	global_load_lds_dwordx4 v132, s[20:21]
	s_add_u32 s100, s20, s58
	s_addc_u32 s101, s21, s59
	s_mov_b32 m0, s26
	s_nop 0
	global_load_lds_dwordx4 v130, s[20:21]
	s_barrier
	s_waitcnt lgkmcnt(0)
	s_waitcnt lgkmcnt(0)
	v_mfma_f32_16x16x32_bf16 v[60:63], v[142:145], v[158:161], v[60:63]
	v_mfma_f32_16x16x32_bf16 v[60:63], v[146:149], v[162:165], v[60:63]
	v_mfma_f32_16x16x32_bf16 v[44:47], v[142:145], v[166:169], v[44:47]
	v_mfma_f32_16x16x32_bf16 v[44:47], v[146:149], v[170:173], v[44:47]
	v_mfma_f32_16x16x32_bf16 v[28:31], v[142:145], v[174:177], v[28:31]
	v_mfma_f32_16x16x32_bf16 v[28:31], v[146:149], v[178:181], v[28:31]
	v_mfma_f32_16x16x32_bf16 v[12:15], v[142:145], v[208:211], v[12:15]
	v_mfma_f32_16x16x32_bf16 v[12:15], v[146:149], v[212:215], v[12:15]
	v_mfma_f32_16x16x32_bf16 v[4:7], v[150:153], v[208:211], v[4:7]
	v_mfma_f32_16x16x32_bf16 v[4:7], v[154:157], v[212:215], v[4:7]
	v_mfma_f32_16x16x32_bf16 v[20:23], v[150:153], v[174:177], v[20:23]
	v_mfma_f32_16x16x32_bf16 v[20:23], v[154:157], v[178:181], v[20:23]
	v_mfma_f32_16x16x32_bf16 v[36:39], v[150:153], v[166:169], v[36:39]
	v_mfma_f32_16x16x32_bf16 v[36:39], v[154:157], v[170:173], v[36:39]
	v_mfma_f32_16x16x32_bf16 v[52:55], v[150:153], v[158:161], v[52:55]
	v_mfma_f32_16x16x32_bf16 v[52:55], v[154:157], v[162:165], v[52:55]
	s_barrier
	s_add_u32 s40, s18, 0x80000
	s_addc_u32 s41, s19, 0
	s_add_i32 s39, s42, s24
	s_mov_b32 m0, s39
	s_nop 0
	global_load_lds_dwordx4 v184, s[40:41]
	s_add_i32 m0, s39, 0x2000
	s_nop 0
	global_load_lds_dwordx4 v128, s[40:41]
	s_waitcnt vmcnt(6)
	s_barrier
; #define PG8_STAGE(bufoff, gbase, voff) do { _Pragma("unroll") for (int _i = 0; _i < 2; ++_i) \
;         __builtin_amdgcn_global_load_lds((const unsigned*)((const char*)(gbase) + (voff)[_i]), (LAS unsigned*)(lds + (bufoff) + ldsw + _i * 8192), 16, 0, 0); } while (0)
; #define PG8_LDA(dst, b, h) do { _Pragma("unroll") for (int m = 0; m < 4; ++m) _Pragma("unroll") for (int k = 0; k < 2; ++k) dst[m][k] = *(const LAS bf16x8*)(lds + PG8_SA(b, h) + aoff + m * 2048 + k * 1024); } while (0)
; #define PG8_LDB(dst, b, h) do { _Pragma("unroll") for (int n = 0; n < 2; ++n) _Pragma("unroll") for (int k = 0; k < 2; ++k) dst[n][k] = *(const LAS bf16x8*)(lds + PG8_SB(b, h) + boff + n * 2048 + k * 1024); } while (0)
; #define PG8_MMA(ai, bj, At, Bt) do { __builtin_amdgcn_s_setprio(1); _Pragma("unroll") for (int m = 0; m < 4; ++m) _Pragma("unroll") for (int n = 0; n < 2; ++n) _Pragma("unroll") for (int k = 0; k < 2; ++k) \
;         acc[ai][bj][m][n] = __builtin_amdgcn_mfma_f32_16x16x32_bf16(Bt[n][k], At[m][k], acc[ai][bj][m][n], 0, 0, 0); __builtin_amdgcn_s_setprio(0); } while (0)
; #define PG8_WAIT_V(n) asm volatile("s_waitcnt vmcnt(" #n ")" ::: "memory")
; #define PG8_WAIT_L(n) asm volatile("s_waitcnt lgkmcnt(" #n ")" ::: "memory")
; #define PG8_BAR __builtin_amdgcn_s_barrier()
; #define PG8_SCHED __builtin_amdgcn_sched_barrier(0)
; template <class Epi>
; __device__ __forceinline__ void gemm_phase(LAS unsigned char* lds, const Gemm g, const StaticOrder& S, const Epi& E) {
;     ...
;             PG8_WAIT_V(6); PG8_BAR; PG8_MMA(1, 1, At, B1); PG8_BAR;
;             PG8_LDB(B0, 1, 0); PG8_SCHED; PG8_LDA(At, 1, 0); PG8_STAGE(PG8_SA(0, 1), a2 + hstep, voffA);
;             PG8_WAIT_L(8); PG8_BAR; PG8_WAIT_L(0); PG8_MMA(0, 0, At, B0); PG8_BAR; PG8_SCHED;
;             PG8_LDB(B1, 1, 1); PG8_STAGE(PG8_SB(1, 0), b3, voffB);
;             PG8_BAR; PG8_WAIT_L(0); PG8_MMA(0, 1, At, B1); PG8_BAR;
;             PG8_LDA(At, 1, 1); PG8_STAGE(PG8_SA(1, 0), a3, voffA);
;             PG8_BAR; PG8_WAIT_L(0); PG8_MMA(1, 0, At, B0); PG8_BAR; PG8_SCHED;
	v_mfma_f32_16x16x32_bf16 v[56:59], v[216:219], v[158:161], v[56:59]
	v_mfma_f32_16x16x32_bf16 v[56:59], v[220:223], v[162:165], v[56:59]
	v_mfma_f32_16x16x32_bf16 v[40:43], v[216:219], v[166:169], v[40:43]
	v_mfma_f32_16x16x32_bf16 v[40:43], v[220:223], v[170:173], v[40:43]
	v_mfma_f32_16x16x32_bf16 v[24:27], v[216:219], v[174:177], v[24:27]
	v_mfma_f32_16x16x32_bf16 v[24:27], v[220:223], v[178:181], v[24:27]
	v_mfma_f32_16x16x32_bf16 v[8:11], v[216:219], v[208:211], v[8:11]
	v_mfma_f32_16x16x32_bf16 v[8:11], v[220:223], v[212:215], v[8:11]
	v_mfma_f32_16x16x32_bf16 v[0:3], v[224:227], v[208:211], v[0:3]
	v_mfma_f32_16x16x32_bf16 v[0:3], v[228:231], v[212:215], v[0:3]
	v_mfma_f32_16x16x32_bf16 v[16:19], v[224:227], v[174:177], v[16:19]
	v_mfma_f32_16x16x32_bf16 v[16:19], v[228:231], v[178:181], v[16:19]
	v_mfma_f32_16x16x32_bf16 v[32:35], v[224:227], v[166:169], v[32:35]
	v_mfma_f32_16x16x32_bf16 v[32:35], v[228:231], v[170:173], v[32:35]
	v_mfma_f32_16x16x32_bf16 v[48:51], v[224:227], v[158:161], v[48:51]
	v_mfma_f32_16x16x32_bf16 v[48:51], v[228:231], v[162:165], v[48:51]
	s_add_i32 s39, 0, 0x18000
	s_barrier
	ds_read_b128 v[142:145], v139 offset:32768
	ds_read_b128 v[146:149], v139 offset:33792
	ds_read_b128 v[150:153], v139 offset:34816
	ds_read_b128 v[154:157], v139 offset:35840
	s_add_u32 s20, s20, 0x80000
	s_addc_u32 s21, s21, 0
	s_mov_b32 m0, s27
	ds_read_b128 v[158:161], v141 offset:32768
	ds_read_b128 v[162:165], v141 offset:33792
	ds_read_b128 v[166:169], v141 offset:34816
	ds_read_b128 v[170:173], v141 offset:35840
	ds_read_b128 v[174:177], v141 offset:36864
	ds_read_b128 v[178:181], v141 offset:37888
	ds_read_b128 v[208:211], v141 offset:38912
	ds_read_b128 v[212:215], v141 offset:39936
	global_load_lds_dwordx4 v132, s[20:21]
	s_mov_b32 m0, s28
	s_nop 0
	global_load_lds_dwordx4 v130, s[20:21]
	s_waitcnt lgkmcnt(8)
	s_barrier
	s_waitcnt lgkmcnt(0)
	s_waitcnt lgkmcnt(0)
	v_mfma_f32_16x16x32_bf16 v[124:127], v[142:145], v[158:161], v[124:127]
	v_mfma_f32_16x16x32_bf16 v[124:127], v[146:149], v[162:165], v[124:127]
	v_mfma_f32_16x16x32_bf16 v[108:111], v[142:145], v[166:169], v[108:111]
	v_mfma_f32_16x16x32_bf16 v[108:111], v[146:149], v[170:173], v[108:111]
	v_mfma_f32_16x16x32_bf16 v[92:95], v[142:145], v[174:177], v[92:95]
	v_mfma_f32_16x16x32_bf16 v[92:95], v[146:149], v[178:181], v[92:95]
	v_mfma_f32_16x16x32_bf16 v[76:79], v[142:145], v[208:211], v[76:79]
	v_mfma_f32_16x16x32_bf16 v[76:79], v[146:149], v[212:215], v[76:79]
	v_mfma_f32_16x16x32_bf16 v[68:71], v[150:153], v[208:211], v[68:71]
	v_mfma_f32_16x16x32_bf16 v[68:71], v[154:157], v[212:215], v[68:71]
	v_mfma_f32_16x16x32_bf16 v[84:87], v[150:153], v[174:177], v[84:87]
	v_mfma_f32_16x16x32_bf16 v[84:87], v[154:157], v[178:181], v[84:87]
	v_mfma_f32_16x16x32_bf16 v[100:103], v[150:153], v[166:169], v[100:103]
	v_mfma_f32_16x16x32_bf16 v[100:103], v[154:157], v[170:173], v[100:103]
	v_mfma_f32_16x16x32_bf16 v[116:119], v[150:153], v[158:161], v[116:119]
	v_mfma_f32_16x16x32_bf16 v[116:119], v[154:157], v[162:165], v[116:119]
	s_barrier
	s_add_i32 s20, 0, 0x1c000
	s_add_i32 s21, s39, s24
	s_mov_b32 m0, s21
	ds_read_b128 v[216:219], v139 offset:49152
	ds_read_b128 v[220:223], v139 offset:50176
	ds_read_b128 v[224:227], v139 offset:51200
	ds_read_b128 v[228:231], v139 offset:52224
	global_load_lds_dwordx4 v184, s[98:99]
	s_add_i32 m0, s21, 0x2000
	s_nop 0
	global_load_lds_dwordx4 v128, s[98:99]
	s_barrier
	s_waitcnt lgkmcnt(0)
	s_waitcnt lgkmcnt(0)
	v_mfma_f32_16x16x32_bf16 v[120:123], v[216:219], v[158:161], v[120:123]
	v_mfma_f32_16x16x32_bf16 v[120:123], v[220:223], v[162:165], v[120:123]
	v_mfma_f32_16x16x32_bf16 v[104:107], v[216:219], v[166:169], v[104:107]
	v_mfma_f32_16x16x32_bf16 v[104:107], v[220:223], v[170:173], v[104:107]
	v_mfma_f32_16x16x32_bf16 v[88:91], v[216:219], v[174:177], v[88:91]
	v_mfma_f32_16x16x32_bf16 v[88:91], v[220:223], v[178:181], v[88:91]
	v_mfma_f32_16x16x32_bf16 v[72:75], v[216:219], v[208:211], v[72:75]
	v_mfma_f32_16x16x32_bf16 v[72:75], v[220:223], v[212:215], v[72:75]
	v_mfma_f32_16x16x32_bf16 v[64:67], v[224:227], v[208:211], v[64:67]
	v_mfma_f32_16x16x32_bf16 v[64:67], v[228:231], v[212:215], v[64:67]
	v_mfma_f32_16x16x32_bf16 v[80:83], v[224:227], v[174:177], v[80:83]
	v_mfma_f32_16x16x32_bf16 v[80:83], v[228:231], v[178:181], v[80:83]
	v_mfma_f32_16x16x32_bf16 v[96:99], v[224:227], v[166:169], v[96:99]
	v_mfma_f32_16x16x32_bf16 v[96:99], v[228:231], v[170:173], v[96:99]
	v_mfma_f32_16x16x32_bf16 v[112:115], v[224:227], v[158:161], v[112:115]
	v_mfma_f32_16x16x32_bf16 v[112:115], v[228:231], v[162:165], v[112:115]
	s_mov_b32 m0, s29
	s_barrier
	ds_read_b128 v[158:161], v141 offset:49152
	ds_read_b128 v[162:165], v141 offset:50176
	ds_read_b128 v[166:169], v141 offset:51200
	ds_read_b128 v[170:173], v141 offset:52224
	ds_read_b128 v[174:177], v141 offset:53248
	ds_read_b128 v[178:181], v141 offset:54272
	ds_read_b128 v[208:211], v141 offset:55296
	ds_read_b128 v[212:215], v141 offset:56320
	global_load_lds_dwordx4 v132, s[100:101]
	s_mov_b32 m0, s30
	s_nop 0
	global_load_lds_dwordx4 v130, s[100:101]
	s_barrier
; __device__ __forceinline__ unsigned pk2(float lo, float hi) { unsigned r; asm("v_cvt_pk_bf16_f32 %0, %1, %2" : "=v"(r) : "v"(lo), "v"(hi)); return r; }
; __device__ __forceinline__ float sigmoidf_(float x) { return __builtin_amdgcn_rcpf(1.0f + __builtin_amdgcn_exp2f(-1.4426950408889634f * x)); }
; #define PG8_STAGE(bufoff, gbase, voff) do { _Pragma("unroll") for (int _i = 0; _i < 2; ++_i) \
;         __builtin_amdgcn_global_load_lds((const unsigned*)((const char*)(gbase) + (voff)[_i]), (LAS unsigned*)(lds + (bufoff) + ldsw + _i * 8192), 16, 0, 0); } while (0)
; #define PG8_MMA(ai, bj, At, Bt) do { __builtin_amdgcn_s_setprio(1); _Pragma("unroll") for (int m = 0; m < 4; ++m) _Pragma("unroll") for (int n = 0; n < 2; ++n) _Pragma("unroll") for (int k = 0; k < 2; ++k) \
;         acc[ai][bj][m][n] = __builtin_amdgcn_mfma_f32_16x16x32_bf16(Bt[n][k], At[m][k], acc[ai][bj][m][n], 0, 0, 0); __builtin_amdgcn_s_setprio(0); } while (0)
; #define PG8_WAIT_V(n) asm volatile("s_waitcnt vmcnt(" #n ")" ::: "memory")
; #define PG8_WAIT_L(n) asm volatile("s_waitcnt lgkmcnt(" #n ")" ::: "memory")
; #define PG8_BAR __builtin_amdgcn_s_barrier()
; #define PG8_SCHED __builtin_amdgcn_sched_barrier(0)
; template <class Epi>
; __device__ __forceinline__ void gemm_phase(LAS unsigned char* lds, const Gemm g, const StaticOrder& S, const Epi& E) {
;     ...
;             PG8_BAR; PG8_WAIT_L(0); PG8_MMA(1, 0, At, B0); PG8_BAR; PG8_SCHED;
;             PG8_STAGE(PG8_SB(1, 1), b3 + hstep, voffB);
;             PG8_WAIT_V(6); PG8_BAR; PG8_MMA(1, 1, At, B1); PG8_BAR;
;         }
;     __device__ __forceinline__ void operator()(const Acc& acc, const Unit& u, int wr, int wc, int fr, int fq) const {
;         const int row0 = u.pm * 256 + wr * 64 + fr, col0 = u.pn * 128 + wc * 32 + 8 * fq;
; #pragma unroll
;         for (int ai = 0; ai < 2; ++ai)
; #pragma unroll
;             for (int m = 0; m < 4; ++m) {
;                 float h[8];
; #pragma unroll
;                 for (int n = 0; n < 2; ++n)
; #pragma unroll
;                     for (int j = 0; j < 4; ++j) { const float gv = acc[ai][0][m][n][j], uv = acc[ai][1][m][n][j]; h[n * 4 + j] = gv * sigmoidf_(gv) * uv; }
;                 u32x4 w; w.x = pk2(h[0], h[1]); w.y = pk2(h[2], h[3]); w.z = pk2(h[4], h[5]); w.w = pk2(h[6], h[7]);
;                 *(u32x4*)(H + (size_t)(row0 + ai * 128 + m * 16) * DFF + col0) = w;
	s_waitcnt lgkmcnt(0)
	s_waitcnt lgkmcnt(0)
	v_mfma_f32_16x16x32_bf16 v[60:63], v[142:145], v[158:161], v[60:63]
	v_mfma_f32_16x16x32_bf16 v[60:63], v[146:149], v[162:165], v[60:63]
	v_mfma_f32_16x16x32_bf16 v[44:47], v[142:145], v[166:169], v[44:47]
	v_mfma_f32_16x16x32_bf16 v[44:47], v[146:149], v[170:173], v[44:47]
	v_mfma_f32_16x16x32_bf16 v[28:31], v[142:145], v[174:177], v[28:31]
	v_mfma_f32_16x16x32_bf16 v[28:31], v[146:149], v[178:181], v[28:31]
	v_mfma_f32_16x16x32_bf16 v[12:15], v[142:145], v[208:211], v[12:15]
	v_mfma_f32_16x16x32_bf16 v[12:15], v[146:149], v[212:215], v[12:15]
	v_mfma_f32_16x16x32_bf16 v[4:7], v[150:153], v[208:211], v[4:7]
	v_mfma_f32_16x16x32_bf16 v[4:7], v[154:157], v[212:215], v[4:7]
	v_mfma_f32_16x16x32_bf16 v[20:23], v[150:153], v[174:177], v[20:23]
	v_mfma_f32_16x16x32_bf16 v[20:23], v[154:157], v[178:181], v[20:23]
	v_mfma_f32_16x16x32_bf16 v[36:39], v[150:153], v[166:169], v[36:39]
	v_mfma_f32_16x16x32_bf16 v[36:39], v[154:157], v[170:173], v[36:39]
	v_mfma_f32_16x16x32_bf16 v[52:55], v[150:153], v[158:161], v[52:55]
	v_mfma_f32_16x16x32_bf16 v[52:55], v[154:157], v[162:165], v[52:55]
	s_barrier
	s_add_u32 s18, s18, 0x80080
	s_addc_u32 s19, s19, 0
	s_add_i32 s20, s20, s24
	s_mov_b32 m0, s20
	s_nop 0
	global_load_lds_dwordx4 v184, s[18:19]
	s_add_i32 m0, s20, 0x2000
	s_nop 0
	global_load_lds_dwordx4 v128, s[18:19]
	s_waitcnt vmcnt(6)
	s_barrier
	v_mfma_f32_16x16x32_bf16 v[56:59], v[216:219], v[158:161], v[56:59]
	v_mfma_f32_16x16x32_bf16 v[56:59], v[220:223], v[162:165], v[56:59]
	v_mfma_f32_16x16x32_bf16 v[40:43], v[216:219], v[166:169], v[40:43]
	v_mfma_f32_16x16x32_bf16 v[40:43], v[220:223], v[170:173], v[40:43]
	v_mfma_f32_16x16x32_bf16 v[24:27], v[216:219], v[174:177], v[24:27]
	v_mfma_f32_16x16x32_bf16 v[24:27], v[220:223], v[178:181], v[24:27]
	v_mfma_f32_16x16x32_bf16 v[8:11], v[216:219], v[208:211], v[8:11]
	v_mfma_f32_16x16x32_bf16 v[8:11], v[220:223], v[212:215], v[8:11]
	v_mfma_f32_16x16x32_bf16 v[0:3], v[224:227], v[208:211], v[0:3]
	v_mfma_f32_16x16x32_bf16 v[0:3], v[228:231], v[212:215], v[0:3]
	v_mfma_f32_16x16x32_bf16 v[16:19], v[224:227], v[174:177], v[16:19]
	v_mfma_f32_16x16x32_bf16 v[16:19], v[228:231], v[178:181], v[16:19]
	v_mfma_f32_16x16x32_bf16 v[32:35], v[224:227], v[166:169], v[32:35]
	v_mfma_f32_16x16x32_bf16 v[32:35], v[228:231], v[170:173], v[32:35]
	v_mfma_f32_16x16x32_bf16 v[48:51], v[224:227], v[158:161], v[48:51]
	v_mfma_f32_16x16x32_bf16 v[48:51], v[228:231], v[162:165], v[48:51]
	s_add_i32 s38, s38, 2
	s_add_u32 s16, s16, 0x100
	s_addc_u32 s17, s17, 0
	s_add_u32 s36, s36, 0x100
	s_addc_u32 s37, s37, 0
	s_cmp_gt_u32 s38, 29
	s_barrier
	s_cbranch_scc0 .LBB0_721
	v_mul_f32_e32 v143, 0xbfb8aa3b, v124
	v_exp_f32_e32 v143, v143
	v_lshl_or_b32 v144, s3, 7, v140
	v_lshl_add_u32 v142, s14, 8, v138
	v_ashrrev_i32_e32 v145, 31, v144
	v_add_f32_e32 v143, 1.0, v143
	v_rcp_f32_e32 v143, v143
	s_movk_i32 s1, 0x2c00
	s_and_b64 vcc, exec, s[6:7]
	s_mov_b32 s3, s0
	v_mul_f32_e32 v124, v124, v143
	v_mul_f32_e32 v120, v124, v120
	v_mul_f32_e32 v124, 0xbfb8aa3b, v125
	v_exp_f32_e32 v124, v124
	s_mov_b32 s14, s8
	s_mov_b64 s[18:19], s[12:13]
	v_add_f32_e32 v124, 1.0, v124
	v_rcp_f32_e32 v124, v124
	s_nop 0
	v_mul_f32_e32 v124, v125, v124
	v_mul_f32_e32 v121, v124, v121
	v_mul_f32_e32 v124, 0xbfb8aa3b, v126
	v_exp_f32_e32 v124, v124
	s_nop 0
	v_add_f32_e32 v124, 1.0, v124
	v_rcp_f32_e32 v124, v124
	s_nop 0
	v_mul_f32_e32 v124, v126, v124
	v_mul_f32_e32 v122, v124, v122
	v_mul_f32_e32 v124, 0xbfb8aa3b, v127
	v_exp_f32_e32 v124, v124
	s_nop 0
	v_add_f32_e32 v124, 1.0, v124
	v_rcp_f32_e32 v124, v124
	s_nop 0
	v_mul_f32_e32 v124, v127, v124
	v_mul_f32_e32 v123, v124, v123
	v_mul_f32_e32 v124, 0xbfb8aa3b, v116
	v_exp_f32_e32 v124, v124
	s_nop 0
	v_add_f32_e32 v124, 1.0, v124
	v_rcp_f32_e32 v124, v124
	s_nop 0
	v_mul_f32_e32 v116, v116, v124
	v_mul_f32_e32 v112, v116, v112
	v_mul_f32_e32 v116, 0xbfb8aa3b, v117
	v_exp_f32_e32 v116, v116
	s_nop 0
	v_add_f32_e32 v116, 1.0, v116
	v_rcp_f32_e32 v116, v116
	s_nop 0
	v_mul_f32_e32 v116, v117, v116
	v_mul_f32_e32 v113, v116, v113
	v_mul_f32_e32 v116, 0xbfb8aa3b, v118
	v_exp_f32_e32 v116, v116
	v_cvt_pk_bf16_f32 v117, v122, v123
	s_nop 0
	v_add_f32_e32 v116, 1.0, v116
	v_rcp_f32_e32 v116, v116
	s_nop 0
	v_mul_f32_e32 v116, v118, v116
	v_mul_f32_e32 v114, v116, v114
	v_mul_f32_e32 v116, 0xbfb8aa3b, v119
	v_exp_f32_e32 v116, v116
	v_cvt_pk_bf16_f32 v118, v112, v113
	v_mov_b64_e32 v[112:113], s[66:67]
	v_add_f32_e32 v116, 1.0, v116
	v_rcp_f32_e32 v116, v116
	s_nop 0
	v_mul_f32_e32 v116, v119, v116
	v_mul_f32_e32 v115, v116, v115
	v_cvt_pk_bf16_f32 v116, v120, v121
	v_cvt_pk_bf16_f32 v119, v114, v115
	v_mad_i64_i32 v[120:121], s[16:17], v142, s1, v[112:113]
	v_lshlrev_b64 v[114:115], 1, v[144:145]
	v_lshl_add_u64 v[120:121], v[120:121], 0, v[114:115]
	global_store_dwordx4 v[120:121], v[116:119], off
	s_nop 1
	v_mul_f32_e32 v116, 0xbfb8aa3b, v108
	v_exp_f32_e32 v116, v116
	s_nop 0
	v_add_f32_e32 v116, 1.0, v116
	v_rcp_f32_e32 v116, v116
	s_nop 0
	v_mul_f32_e32 v108, v108, v116
	v_mul_f32_e32 v104, v108, v104
	v_mul_f32_e32 v108, 0xbfb8aa3b, v109
	v_exp_f32_e32 v108, v108
	s_nop 0
	v_add_f32_e32 v108, 1.0, v108
	v_rcp_f32_e32 v108, v108
	s_nop 0
	v_mul_f32_e32 v108, v109, v108
	v_mul_f32_e32 v105, v108, v105
	v_mul_f32_e32 v108, 0xbfb8aa3b, v110
	v_exp_f32_e32 v108, v108
	s_nop 0
	v_add_f32_e32 v108, 1.0, v108
	v_rcp_f32_e32 v108, v108
	s_nop 0
	v_mul_f32_e32 v108, v110, v108
	v_mul_f32_e32 v106, v108, v106
	v_mul_f32_e32 v108, 0xbfb8aa3b, v111
	v_exp_f32_e32 v108, v108
	s_nop 0
	v_add_f32_e32 v108, 1.0, v108
	v_rcp_f32_e32 v108, v108
	s_nop 0
; __device__ __forceinline__ unsigned pk2(float lo, float hi) { unsigned r; asm("v_cvt_pk_bf16_f32 %0, %1, %2" : "=v"(r) : "v"(lo), "v"(hi)); return r; }
; __device__ __forceinline__ float sigmoidf_(float x) { return __builtin_amdgcn_rcpf(1.0f + __builtin_amdgcn_exp2f(-1.4426950408889634f * x)); }
;     __device__ __forceinline__ void operator()(const Acc& acc, const Unit& u, int wr, int wc, int fr, int fq) const {
;     ...
;         for (int ai = 0; ai < 2; ++ai)
; #pragma unroll
;             for (int m = 0; m < 4; ++m) {
;                 float h[8];
; #pragma unroll
;                 for (int n = 0; n < 2; ++n)
; #pragma unroll
;                     for (int j = 0; j < 4; ++j) { const float gv = acc[ai][0][m][n][j], uv = acc[ai][1][m][n][j]; h[n * 4 + j] = gv * sigmoidf_(gv) * uv; }
;                 u32x4 w; w.x = pk2(h[0], h[1]); w.y = pk2(h[2], h[3]); w.z = pk2(h[4], h[5]); w.w = pk2(h[6], h[7]);
;                 *(u32x4*)(H + (size_t)(row0 + ai * 128 + m * 16) * DFF + col0) = w;
	v_mul_f32_e32 v108, v111, v108
	v_mul_f32_e32 v107, v108, v107
	v_mul_f32_e32 v108, 0xbfb8aa3b, v100
	v_exp_f32_e32 v108, v108
	s_nop 0
	v_add_f32_e32 v108, 1.0, v108
	v_rcp_f32_e32 v108, v108
	s_nop 0
	v_mul_f32_e32 v100, v100, v108
	v_mul_f32_e32 v100, v100, v96
	v_mul_f32_e32 v96, 0xbfb8aa3b, v101
	v_exp_f32_e32 v96, v96
	s_nop 0
	v_add_f32_e32 v96, 1.0, v96
	v_rcp_f32_e32 v96, v96
	s_nop 0
	v_mul_f32_e32 v96, v101, v96
	v_mul_f32_e32 v101, v96, v97
	v_mul_f32_e32 v96, 0xbfb8aa3b, v102
	v_exp_f32_e32 v96, v96
	v_cvt_pk_bf16_f32 v97, v106, v107
	s_nop 0
	v_add_f32_e32 v96, 1.0, v96
	v_rcp_f32_e32 v96, v96
	s_nop 0
	v_mul_f32_e32 v96, v102, v96
	v_mul_f32_e32 v102, v96, v98
	v_mul_f32_e32 v96, 0xbfb8aa3b, v103
	v_exp_f32_e32 v96, v96
	v_cvt_pk_bf16_f32 v98, v100, v101
	v_or_b32_e32 v100, 16, v142
	v_mad_i64_i32 v[100:101], s[16:17], v100, s1, v[112:113]
	v_add_f32_e32 v96, 1.0, v96
	v_rcp_f32_e32 v96, v96
	v_lshl_add_u64 v[100:101], v[100:101], 0, v[114:115]
	v_mul_f32_e32 v96, v103, v96
	v_mul_f32_e32 v99, v96, v99
	v_cvt_pk_bf16_f32 v96, v104, v105
	v_cvt_pk_bf16_f32 v99, v102, v99
	global_store_dwordx4 v[100:101], v[96:99], off
	s_nop 1
	v_mul_f32_e32 v96, 0xbfb8aa3b, v92
	v_exp_f32_e32 v96, v96
	s_nop 0
	v_add_f32_e32 v96, 1.0, v96
	v_rcp_f32_e32 v96, v96
	s_nop 0
	v_mul_f32_e32 v92, v92, v96
	v_mul_f32_e32 v88, v92, v88
	v_mul_f32_e32 v92, 0xbfb8aa3b, v93
	v_exp_f32_e32 v92, v92
	s_nop 0
	v_add_f32_e32 v92, 1.0, v92
	v_rcp_f32_e32 v92, v92
	s_nop 0
	v_mul_f32_e32 v92, v93, v92
	v_mul_f32_e32 v89, v92, v89
	v_mul_f32_e32 v92, 0xbfb8aa3b, v94
	v_exp_f32_e32 v92, v92
	s_nop 0
	v_add_f32_e32 v92, 1.0, v92
	v_rcp_f32_e32 v92, v92
	s_nop 0
	v_mul_f32_e32 v92, v94, v92
	v_mul_f32_e32 v90, v92, v90
	v_mul_f32_e32 v92, 0xbfb8aa3b, v95
	v_exp_f32_e32 v92, v92
	s_nop 0
	v_add_f32_e32 v92, 1.0, v92
	v_rcp_f32_e32 v92, v92
	s_nop 0
	v_mul_f32_e32 v92, v95, v92
	v_mul_f32_e32 v91, v92, v91
	v_mul_f32_e32 v92, 0xbfb8aa3b, v84
	v_exp_f32_e32 v92, v92
	s_nop 0
	v_add_f32_e32 v92, 1.0, v92
	v_rcp_f32_e32 v92, v92
	s_nop 0
	v_mul_f32_e32 v84, v84, v92
	v_mul_f32_e32 v84, v84, v80
	v_mul_f32_e32 v80, 0xbfb8aa3b, v85
	v_exp_f32_e32 v80, v80
	s_nop 0
	v_add_f32_e32 v80, 1.0, v80
	v_rcp_f32_e32 v80, v80
	s_nop 0
	v_mul_f32_e32 v80, v85, v80
	v_mul_f32_e32 v85, v80, v81
	v_mul_f32_e32 v80, 0xbfb8aa3b, v86
	v_exp_f32_e32 v80, v80
	v_cvt_pk_bf16_f32 v81, v90, v91
	s_nop 0
	v_add_f32_e32 v80, 1.0, v80
	v_rcp_f32_e32 v80, v80
	s_nop 0
	v_mul_f32_e32 v80, v86, v80
	v_mul_f32_e32 v86, v80, v82
	v_mul_f32_e32 v80, 0xbfb8aa3b, v87
	v_exp_f32_e32 v80, v80
	v_cvt_pk_bf16_f32 v82, v84, v85
	v_or_b32_e32 v84, 32, v142
	v_mad_i64_i32 v[84:85], s[16:17], v84, s1, v[112:113]
	v_add_f32_e32 v80, 1.0, v80
	v_rcp_f32_e32 v80, v80
	v_lshl_add_u64 v[84:85], v[84:85], 0, v[114:115]
	v_mul_f32_e32 v80, v87, v80
	v_mul_f32_e32 v83, v80, v83
	v_cvt_pk_bf16_f32 v80, v88, v89
	v_cvt_pk_bf16_f32 v83, v86, v83
	global_store_dwordx4 v[84:85], v[80:83], off
	s_nop 1
	v_mul_f32_e32 v80, 0xbfb8aa3b, v76
	v_exp_f32_e32 v80, v80
	s_nop 0
	v_add_f32_e32 v80, 1.0, v80
	v_rcp_f32_e32 v80, v80
	s_nop 0
	v_mul_f32_e32 v76, v76, v80
	v_mul_f32_e32 v72, v76, v72
	v_mul_f32_e32 v76, 0xbfb8aa3b, v77
	v_exp_f32_e32 v76, v76
	s_nop 0
	v_add_f32_e32 v76, 1.0, v76
	v_rcp_f32_e32 v76, v76
	s_nop 0
	v_mul_f32_e32 v76, v77, v76
	v_mul_f32_e32 v73, v76, v73
	v_mul_f32_e32 v76, 0xbfb8aa3b, v78
	v_exp_f32_e32 v76, v76
	s_nop 0
	v_add_f32_e32 v76, 1.0, v76
	v_rcp_f32_e32 v76, v76
	s_nop 0
	v_mul_f32_e32 v76, v78, v76
	v_mul_f32_e32 v74, v76, v74
	v_mul_f32_e32 v76, 0xbfb8aa3b, v79
	v_exp_f32_e32 v76, v76
	s_nop 0
	v_add_f32_e32 v76, 1.0, v76
	v_rcp_f32_e32 v76, v76
	s_nop 0
	v_mul_f32_e32 v76, v79, v76
	v_mul_f32_e32 v75, v76, v75
	v_mul_f32_e32 v76, 0xbfb8aa3b, v68
	v_exp_f32_e32 v76, v76
	s_nop 0
	v_add_f32_e32 v76, 1.0, v76
	v_rcp_f32_e32 v76, v76
	s_nop 0
	v_mul_f32_e32 v68, v68, v76
	v_mul_f32_e32 v68, v68, v64
	v_mul_f32_e32 v64, 0xbfb8aa3b, v69
	v_exp_f32_e32 v64, v64
	s_nop 0
	v_add_f32_e32 v64, 1.0, v64
	v_rcp_f32_e32 v64, v64
	s_nop 0
	v_mul_f32_e32 v64, v69, v64
	v_mul_f32_e32 v69, v64, v65
	v_mul_f32_e32 v64, 0xbfb8aa3b, v70
	v_exp_f32_e32 v64, v64
	v_cvt_pk_bf16_f32 v65, v74, v75
	s_nop 0
	v_add_f32_e32 v64, 1.0, v64
	v_rcp_f32_e32 v64, v64
	s_nop 0
	v_mul_f32_e32 v64, v70, v64
	v_mul_f32_e32 v70, v64, v66
	v_mul_f32_e32 v64, 0xbfb8aa3b, v71
	v_exp_f32_e32 v64, v64
	v_cvt_pk_bf16_f32 v66, v68, v69
	v_or_b32_e32 v68, 48, v142
	v_mad_i64_i32 v[68:69], s[16:17], v68, s1, v[112:113]
	v_add_f32_e32 v64, 1.0, v64
	v_rcp_f32_e32 v64, v64
	v_lshl_add_u64 v[68:69], v[68:69], 0, v[114:115]
	v_mul_f32_e32 v64, v71, v64
	v_mul_f32_e32 v67, v64, v67
	v_cvt_pk_bf16_f32 v64, v72, v73
	v_cvt_pk_bf16_f32 v67, v70, v67
	global_store_dwordx4 v[68:69], v[64:67], off
	s_nop 1
	v_mul_f32_e32 v65, 0xbfb8aa3b, v60
	v_exp_f32_e32 v65, v65
	v_add_u32_e32 v64, 0x80, v142
	v_add_f32_e32 v65, 1.0, v65
	v_rcp_f32_e32 v65, v65
	s_nop 0
	v_mul_f32_e32 v60, v60, v65
	v_mul_f32_e32 v56, v60, v56
	v_mul_f32_e32 v60, 0xbfb8aa3b, v61
	v_exp_f32_e32 v60, v60
	s_nop 0
	v_add_f32_e32 v60, 1.0, v60
	v_rcp_f32_e32 v60, v60
	s_nop 0
	v_mul_f32_e32 v60, v61, v60
	v_mul_f32_e32 v57, v60, v57
	v_mul_f32_e32 v60, 0xbfb8aa3b, v62
	v_exp_f32_e32 v60, v60
	s_nop 0
	v_add_f32_e32 v60, 1.0, v60
	v_rcp_f32_e32 v60, v60
	s_nop 0
	v_mul_f32_e32 v60, v62, v60
	v_mul_f32_e32 v58, v60, v58
	v_mul_f32_e32 v60, 0xbfb8aa3b, v63
	v_exp_f32_e32 v60, v60
	s_nop 0
	v_add_f32_e32 v60, 1.0, v60
	v_rcp_f32_e32 v60, v60
	s_nop 0
	v_mul_f32_e32 v60, v63, v60
	v_mul_f32_e32 v59, v60, v59
	v_mul_f32_e32 v60, 0xbfb8aa3b, v52
	v_exp_f32_e32 v60, v60
	s_nop 0
; __device__ __forceinline__ unsigned pk2(float lo, float hi) { unsigned r; asm("v_cvt_pk_bf16_f32 %0, %1, %2" : "=v"(r) : "v"(lo), "v"(hi)); return r; }
; __device__ __forceinline__ float sigmoidf_(float x) { return __builtin_amdgcn_rcpf(1.0f + __builtin_amdgcn_exp2f(-1.4426950408889634f * x)); }
; #define PG8_WAIT_V(n) asm volatile("s_waitcnt vmcnt(" #n ")" ::: "memory")
; #define PG8_BAR __builtin_amdgcn_s_barrier()
; template <class Epi>
; __device__ __forceinline__ void gemm_phase(LAS unsigned char* lds, const Gemm g, const StaticOrder& S, const Epi& E) {
;     ...
;         if (!has_next) break;
; #pragma unroll
;         for (int a = 0; a < 2; ++a)
; #pragma unroll
;             for (int b = 0; b < 2; ++b)
; #pragma unroll
;                 for (int m = 0; m < 4; ++m)
; #pragma unroll
;                     for (int n = 0; n < 2; ++n) acc[a][b][m][n] = (f32x4){0.f, 0.f, 0.f, 0.f};
;         cur = nxt; cA = nA; cB = nB; ++ui;
;     }
;     PG8_WAIT_V(0);
;     if (wr == 0) PG8_BAR;
;     PG8_BAR;
;     __device__ __forceinline__ void operator()(const Acc& acc, const Unit& u, int wr, int wc, int fr, int fq) const {
;     ...
;         for (int ai = 0; ai < 2; ++ai)
; #pragma unroll
;             for (int m = 0; m < 4; ++m) {
;                 float h[8];
; #pragma unroll
;                 for (int n = 0; n < 2; ++n)
; #pragma unroll
;                     for (int j = 0; j < 4; ++j) { const float gv = acc[ai][0][m][n][j], uv = acc[ai][1][m][n][j]; h[n * 4 + j] = gv * sigmoidf_(gv) * uv; }
;                 u32x4 w; w.x = pk2(h[0], h[1]); w.y = pk2(h[2], h[3]); w.z = pk2(h[4], h[5]); w.w = pk2(h[6], h[7]);
;                 *(u32x4*)(H + (size_t)(row0 + ai * 128 + m * 16) * DFF + col0) = w;
	v_add_f32_e32 v60, 1.0, v60
	v_rcp_f32_e32 v60, v60
	s_nop 0
	v_mul_f32_e32 v52, v52, v60
	v_mul_f32_e32 v52, v52, v48
	v_mul_f32_e32 v48, 0xbfb8aa3b, v53
	v_exp_f32_e32 v48, v48
	s_nop 0
	v_add_f32_e32 v48, 1.0, v48
	v_rcp_f32_e32 v48, v48
	s_nop 0
	v_mul_f32_e32 v48, v53, v48
	v_mul_f32_e32 v53, v48, v49
	v_mul_f32_e32 v48, 0xbfb8aa3b, v54
	v_exp_f32_e32 v48, v48
	v_cvt_pk_bf16_f32 v49, v58, v59
	s_nop 0
	v_add_f32_e32 v48, 1.0, v48
	v_rcp_f32_e32 v48, v48
	s_nop 0
	v_mul_f32_e32 v48, v54, v48
	v_mul_f32_e32 v54, v48, v50
	v_mul_f32_e32 v48, 0xbfb8aa3b, v55
	v_exp_f32_e32 v48, v48
	v_cvt_pk_bf16_f32 v50, v52, v53
	v_mad_i64_i32 v[52:53], s[16:17], v64, s1, v[112:113]
	v_add_f32_e32 v48, 1.0, v48
	v_rcp_f32_e32 v48, v48
	v_lshl_add_u64 v[52:53], v[52:53], 0, v[114:115]
	v_mul_f32_e32 v48, v55, v48
	v_mul_f32_e32 v51, v48, v51
	v_cvt_pk_bf16_f32 v48, v56, v57
	v_cvt_pk_bf16_f32 v51, v54, v51
	global_store_dwordx4 v[52:53], v[48:51], off
	s_nop 1
	v_mul_f32_e32 v48, 0xbfb8aa3b, v44
	v_exp_f32_e32 v48, v48
	s_nop 0
	v_add_f32_e32 v48, 1.0, v48
	v_rcp_f32_e32 v48, v48
	s_nop 0
	v_mul_f32_e32 v44, v44, v48
	v_mul_f32_e32 v40, v44, v40
	v_mul_f32_e32 v44, 0xbfb8aa3b, v45
	v_exp_f32_e32 v44, v44
	s_nop 0
	v_add_f32_e32 v44, 1.0, v44
	v_rcp_f32_e32 v44, v44
	s_nop 0
	v_mul_f32_e32 v44, v45, v44
	v_mul_f32_e32 v41, v44, v41
	v_mul_f32_e32 v44, 0xbfb8aa3b, v46
	v_exp_f32_e32 v44, v44
	s_nop 0
	v_add_f32_e32 v44, 1.0, v44
	v_rcp_f32_e32 v44, v44
	s_nop 0
	v_mul_f32_e32 v44, v46, v44
	v_mul_f32_e32 v42, v44, v42
	v_mul_f32_e32 v44, 0xbfb8aa3b, v47
	v_exp_f32_e32 v44, v44
	s_nop 0
	v_add_f32_e32 v44, 1.0, v44
	v_rcp_f32_e32 v44, v44
	s_nop 0
	v_mul_f32_e32 v44, v47, v44
	v_mul_f32_e32 v43, v44, v43
	v_mul_f32_e32 v44, 0xbfb8aa3b, v36
	v_exp_f32_e32 v44, v44
	s_nop 0
	v_add_f32_e32 v44, 1.0, v44
	v_rcp_f32_e32 v44, v44
	s_nop 0
	v_mul_f32_e32 v36, v36, v44
	v_mul_f32_e32 v36, v36, v32
	v_mul_f32_e32 v32, 0xbfb8aa3b, v37
	v_exp_f32_e32 v32, v32
	s_nop 0
	v_add_f32_e32 v32, 1.0, v32
	v_rcp_f32_e32 v32, v32
	s_nop 0
	v_mul_f32_e32 v32, v37, v32
	v_mul_f32_e32 v37, v32, v33
	v_mul_f32_e32 v32, 0xbfb8aa3b, v38
	v_exp_f32_e32 v32, v32
	v_cvt_pk_bf16_f32 v33, v42, v43
	s_nop 0
	v_add_f32_e32 v32, 1.0, v32
	v_rcp_f32_e32 v32, v32
	s_nop 0
	v_mul_f32_e32 v32, v38, v32
	v_mul_f32_e32 v38, v32, v34
	v_mul_f32_e32 v32, 0xbfb8aa3b, v39
	v_exp_f32_e32 v32, v32
	v_cvt_pk_bf16_f32 v34, v36, v37
	v_add_u32_e32 v36, 0x90, v142
	v_mad_i64_i32 v[36:37], s[16:17], v36, s1, v[112:113]
	v_add_f32_e32 v32, 1.0, v32
	v_rcp_f32_e32 v32, v32
	v_lshl_add_u64 v[36:37], v[36:37], 0, v[114:115]
	v_mul_f32_e32 v32, v39, v32
	v_mul_f32_e32 v35, v32, v35
	v_cvt_pk_bf16_f32 v32, v40, v41
	v_cvt_pk_bf16_f32 v35, v38, v35
	global_store_dwordx4 v[36:37], v[32:35], off
	s_nop 1
	v_mul_f32_e32 v32, 0xbfb8aa3b, v28
	v_exp_f32_e32 v32, v32
	s_nop 0
	v_add_f32_e32 v32, 1.0, v32
	v_rcp_f32_e32 v32, v32
	s_nop 0
	v_mul_f32_e32 v28, v28, v32
	v_mul_f32_e32 v24, v28, v24
	v_mul_f32_e32 v28, 0xbfb8aa3b, v29
	v_exp_f32_e32 v28, v28
	s_nop 0
	v_add_f32_e32 v28, 1.0, v28
	v_rcp_f32_e32 v28, v28
	s_nop 0
	v_mul_f32_e32 v28, v29, v28
	v_mul_f32_e32 v25, v28, v25
	v_mul_f32_e32 v28, 0xbfb8aa3b, v30
	v_exp_f32_e32 v28, v28
	s_nop 0
	v_add_f32_e32 v28, 1.0, v28
	v_rcp_f32_e32 v28, v28
	s_nop 0
	v_mul_f32_e32 v28, v30, v28
	v_mul_f32_e32 v26, v28, v26
	v_mul_f32_e32 v28, 0xbfb8aa3b, v31
	v_exp_f32_e32 v28, v28
	s_nop 0
	v_add_f32_e32 v28, 1.0, v28
	v_rcp_f32_e32 v28, v28
	s_nop 0
	v_mul_f32_e32 v28, v31, v28
	v_mul_f32_e32 v27, v28, v27
	v_mul_f32_e32 v28, 0xbfb8aa3b, v20
	v_exp_f32_e32 v28, v28
	s_nop 0
	v_add_f32_e32 v28, 1.0, v28
	v_rcp_f32_e32 v28, v28
	s_nop 0
	v_mul_f32_e32 v20, v20, v28
	v_mul_f32_e32 v20, v20, v16
	v_mul_f32_e32 v16, 0xbfb8aa3b, v21
	v_exp_f32_e32 v16, v16
	s_nop 0
	v_add_f32_e32 v16, 1.0, v16
	v_rcp_f32_e32 v16, v16
	s_nop 0
	v_mul_f32_e32 v16, v21, v16
	v_mul_f32_e32 v21, v16, v17
	v_mul_f32_e32 v16, 0xbfb8aa3b, v22
	v_exp_f32_e32 v16, v16
	v_cvt_pk_bf16_f32 v17, v26, v27
	s_nop 0
	v_add_f32_e32 v16, 1.0, v16
	v_rcp_f32_e32 v16, v16
	s_nop 0
	v_mul_f32_e32 v16, v22, v16
	v_mul_f32_e32 v22, v16, v18
	v_mul_f32_e32 v16, 0xbfb8aa3b, v23
	v_exp_f32_e32 v16, v16
	v_cvt_pk_bf16_f32 v18, v20, v21
	v_add_u32_e32 v20, 0xa0, v142
	v_mad_i64_i32 v[20:21], s[16:17], v20, s1, v[112:113]
	v_add_f32_e32 v16, 1.0, v16
	v_rcp_f32_e32 v16, v16
	v_lshl_add_u64 v[20:21], v[20:21], 0, v[114:115]
	v_mul_f32_e32 v16, v23, v16
	v_mul_f32_e32 v19, v16, v19
	v_cvt_pk_bf16_f32 v16, v24, v25
	v_cvt_pk_bf16_f32 v19, v22, v19
	global_store_dwordx4 v[20:21], v[16:19], off
	s_nop 1
	v_mul_f32_e32 v16, 0xbfb8aa3b, v12
	v_exp_f32_e32 v16, v16
	s_nop 0
	v_add_f32_e32 v16, 1.0, v16
	v_rcp_f32_e32 v16, v16
	s_nop 0
	v_mul_f32_e32 v12, v12, v16
	v_mul_f32_e32 v8, v12, v8
	v_mul_f32_e32 v12, 0xbfb8aa3b, v13
	v_exp_f32_e32 v12, v12
	s_nop 0
	v_add_f32_e32 v12, 1.0, v12
	v_rcp_f32_e32 v12, v12
	s_nop 0
	v_mul_f32_e32 v12, v13, v12
	v_mul_f32_e32 v9, v12, v9
	v_mul_f32_e32 v12, 0xbfb8aa3b, v14
	v_exp_f32_e32 v12, v12
	s_nop 0
	v_add_f32_e32 v12, 1.0, v12
	v_rcp_f32_e32 v12, v12
	s_nop 0
	v_mul_f32_e32 v12, v14, v12
	v_mul_f32_e32 v10, v12, v10
	v_mul_f32_e32 v12, 0xbfb8aa3b, v15
	v_exp_f32_e32 v12, v12
	s_nop 0
	v_add_f32_e32 v12, 1.0, v12
	v_rcp_f32_e32 v12, v12
	s_nop 0
	v_mul_f32_e32 v12, v15, v12
	v_mul_f32_e32 v11, v12, v11
	v_mul_f32_e32 v12, 0xbfb8aa3b, v4
	v_exp_f32_e32 v12, v12
	s_nop 0
	v_add_f32_e32 v12, 1.0, v12
	v_rcp_f32_e32 v12, v12
	s_nop 0
	v_mul_f32_e32 v4, v4, v12
	v_mul_f32_e32 v4, v4, v0
	v_mul_f32_e32 v0, 0xbfb8aa3b, v5
	v_exp_f32_e32 v0, v0
	s_nop 0
	v_add_f32_e32 v0, 1.0, v0
	v_rcp_f32_e32 v0, v0
	s_nop 0
	v_mul_f32_e32 v0, v5, v0
	v_mul_f32_e32 v5, v0, v1
	v_mul_f32_e32 v0, 0xbfb8aa3b, v6
	v_exp_f32_e32 v0, v0
	v_cvt_pk_bf16_f32 v1, v10, v11
	s_nop 0
	v_add_f32_e32 v0, 1.0, v0
	v_rcp_f32_e32 v0, v0
	s_nop 0
	v_mul_f32_e32 v0, v6, v0
	v_mul_f32_e32 v6, v0, v2
	v_mul_f32_e32 v0, 0xbfb8aa3b, v7
	v_exp_f32_e32 v0, v0
	v_cvt_pk_bf16_f32 v2, v4, v5
	v_add_u32_e32 v4, 0xb0, v142
	v_mad_i64_i32 v[4:5], s[16:17], v4, s1, v[112:113]
	v_add_f32_e32 v0, 1.0, v0
	v_rcp_f32_e32 v0, v0
	v_lshl_add_u64 v[4:5], v[4:5], 0, v[114:115]
	s_mov_b64 s[16:17], s[10:11]
	v_mul_f32_e32 v0, v7, v0
	v_mul_f32_e32 v3, v0, v3
	v_cvt_pk_bf16_f32 v0, v8, v9
	v_cvt_pk_bf16_f32 v3, v6, v3
	global_store_dwordx4 v[4:5], v[0:3], off
	s_cbranch_vccz .LBB0_718
	s_waitcnt vmcnt(0)
	s_cmpk_gt_u32 s23, 0xff
	s_cbranch_scc1 .LBB0_725
	s_barrier
